# v22 + sample-scan always-true masks and dead address code removed + rw_pre per-lane parameter loads hoisted out of token loop (54 regs), vmcnt recounted
# speedup vs baseline: 1.0174x; 1.0072x over previous
; DEV float bf2f(bf16_t b) { return __uint_as_float(((unsigned)b) << 16); }
; DEV void phase_rw_pre(const Params& p) {
;     ...
;   for (int t = gw; t < NTOK; t += nw) {
;     int tb, T;
;     seq_of_token(t, tb, T);
;     const bool hp = t > tb, hn = t < tb + T - 1;
;     const int op = hp ? -RW_LD : 0, on = hn ? RW_LD : 0;
;     const bf16_t* row = proj + (size_t)t * RW_LD + lane;
;     bf16_t raw[8][7];
; #pragma unroll
;     for (int h = 0; h < 8; ++h) {
;       raw[h][0] = row[h * 64];
;       raw[h][1] = row[h * 64 + op];
;       raw[h][2] = row[h * 64 + on];
;       raw[h][3] = row[512 + h * 64];
;       raw[h][4] = row[512 + h * 64 + op];
;       raw[h][5] = row[512 + h * 64 + on];
;       raw[h][6] = ap[(size_t)t * 512 + h * 64 + lane];
;     }
; #pragma unroll
;     for (int h = 0; h < 8; ++h) {
;       const int hc = h * 64 + lane;
;       float x = bf2f(raw[h][0]);
;       const float r = x + p.in[14][hc] * ((hp ? bf2f(raw[h][1]) : 0.f) - x) + p.in[15][hc] * ((hn ? bf2f(raw[h][2]) : 0.f) - x);
;       x = bf2f(raw[h][3]);
;       const float kr = x + p.in[14][512 + hc] * ((hp ? bf2f(raw[h][4]) : 0.f) - x) + p.in[15][512 + hc] * ((hn ? bf2f(raw[h][5]) : 0.f) - x);
;       const float a = bf2f(raw[h][6]);
;       const float kkr = kr * p.in[23][hc];
;       const float inv = rsqrtf(fmaxf(wave_sum_dpp(kkr * kkr), 1e-24f));
;       const float kk = kkr * inv;
;       const float k2 = kr * (1.f + (a - 1.f) * p.in[24][hc]);
;       const float kar = wave_sum_dpp(kk * a * r);
;       const float bo = wave_sum_dpp(r * k2 * p.in[25][hc]);
.LBB0_1847:
	s_and_saveexec_b64 s[78:79], s[6:7]
	s_cbranch_execz .LBB0_1866
	global_load_dword v110, v[6:7], off
	global_load_dword v111, v[8:9], off
	global_load_dword v112, v[6:7], off offset:2048
	global_load_dword v113, v[8:9], off offset:2048
	global_load_dword v114, v[12:13], off
	global_load_dword v115, v[10:11], off
	global_load_dword v116, v[14:15], off
	global_load_dword v117, v[6:7], off offset:256
	global_load_dword v118, v[8:9], off offset:256
	global_load_dword v119, v[12:13], off offset:256
	global_load_dword v120, v[6:7], off offset:2304
	global_load_dword v121, v[8:9], off offset:2304
	global_load_dword v122, v[10:11], off offset:256
	global_load_dword v123, v[14:15], off offset:256
	global_load_dword v124, v[6:7], off offset:512
	global_load_dword v125, v[8:9], off offset:512
	global_load_dword v126, v[12:13], off offset:512
	global_load_dword v127, v[6:7], off offset:2560
	global_load_dword v128, v[8:9], off offset:2560
	global_load_dword v129, v[10:11], off offset:512
	global_load_dword v130, v[14:15], off offset:512
	global_load_dword v131, v[6:7], off offset:768
	global_load_dword v132, v[8:9], off offset:768
	global_load_dword v133, v[12:13], off offset:768
	global_load_dword v134, v[6:7], off offset:2816
	global_load_dword v136, v[8:9], off offset:2816
	global_load_dword v137, v[10:11], off offset:768
	global_load_dword v138, v[14:15], off offset:768
	global_load_dword v139, v[6:7], off offset:1024
	global_load_dword v142, v[8:9], off offset:1024
	global_load_dword v143, v[12:13], off offset:1024
	global_load_dword v144, v[6:7], off offset:3072
	global_load_dword v145, v[8:9], off offset:3072
	global_load_dword v146, v[10:11], off offset:1024
	global_load_dword v147, v[14:15], off offset:1024
	global_load_dword v148, v[6:7], off offset:1280
	global_load_dword v149, v[8:9], off offset:1280
	global_load_dword v150, v[12:13], off offset:1280
	global_load_dword v151, v[6:7], off offset:3328
	global_load_dword v152, v[8:9], off offset:3328
	global_load_dword v153, v[10:11], off offset:1280
	global_load_dword v154, v[14:15], off offset:1280
	global_load_dword v155, v[6:7], off offset:1536
	global_load_dword v156, v[8:9], off offset:1536
	global_load_dword v157, v[12:13], off offset:1536
	global_load_dword v158, v[6:7], off offset:3584
	global_load_dword v159, v[8:9], off offset:3584
	global_load_dword v160, v[10:11], off offset:1536
	global_load_dword v161, v[14:15], off offset:1536
	global_load_dword v162, v[6:7], off offset:1792
	global_load_dword v163, v[8:9], off offset:1792
	global_load_dword v164, v[12:13], off offset:1792
	global_load_dword v165, v[10:11], off offset:1792
	global_load_dword v166, v[14:15], off offset:1792
	s_waitcnt vmcnt(0)
	s_mov_b64 s[84:85], 0
	v_mov_b64_e32 v[26:27], v[20:21]
	v_mov_b64_e32 v[28:29], v[24:25]
	v_mov_b64_e32 v[30:31], v[22:23]
	v_mov_b32_e32 v49, v4
	s_branch .LBB0_1850

; DEV float bf2f(bf16_t b) { return __uint_as_float(((unsigned)b) << 16); }
; DEV void phase_rw_pre(const Params& p) {
;     ...
;   for (int t = gw; t < NTOK; t += nw) {
;     int tb, T;
;     seq_of_token(t, tb, T);
;     const bool hp = t > tb, hn = t < tb + T - 1;
;     const int op = hp ? -RW_LD : 0, on = hn ? RW_LD : 0;
;     const bf16_t* row = proj + (size_t)t * RW_LD + lane;
;     bf16_t raw[8][7];
; #pragma unroll
;     for (int h = 0; h < 8; ++h) {
;       raw[h][0] = row[h * 64];
;       raw[h][1] = row[h * 64 + op];
;       raw[h][2] = row[h * 64 + on];
;       raw[h][3] = row[512 + h * 64];
;       raw[h][4] = row[512 + h * 64 + op];
;       raw[h][5] = row[512 + h * 64 + on];
;       raw[h][6] = ap[(size_t)t * 512 + h * 64 + lane];
;     }
; #pragma unroll
;     for (int h = 0; h < 8; ++h) {
;       const int hc = h * 64 + lane;
;       float x = bf2f(raw[h][0]);
;       const float r = x + p.in[14][hc] * ((hp ? bf2f(raw[h][1]) : 0.f) - x) + p.in[15][hc] * ((hn ? bf2f(raw[h][2]) : 0.f) - x);
;       x = bf2f(raw[h][3]);
;       const float kr = x + p.in[14][512 + hc] * ((hp ? bf2f(raw[h][4]) : 0.f) - x) + p.in[15][512 + hc] * ((hn ? bf2f(raw[h][5]) : 0.f) - x);
;       const float a = bf2f(raw[h][6]);
;       const float kkr = kr * p.in[23][hc];
;       const float inv = rsqrtf(fmaxf(wave_sum_dpp(kkr * kkr), 1e-24f));
;       const float kk = kkr * inv;
;       const float k2 = kr * (1.f + (a - 1.f) * p.in[24][hc]);
;       const float kar = wave_sum_dpp(kk * a * r);
;       const float bo = wave_sum_dpp(r * k2 * p.in[25][hc]);
;       if (lane == 0) *(float4*)(scal + ((size_t)t * 8 + h) * 4) = make_float4(inv, kar, bo, 0.f);
.LBB0_1850:
	v_readlane_b32 s86, v250, 55
	v_readlane_b32 s87, v250, 56
	s_movk_i32 s1, 0x4000
	s_load_dwordx8 s[88:95], s[86:87], 0x140
	v_cmp_gt_i32_e32 vcc, s1, v49
	s_mov_b32 s1, 0x18900000
	s_waitcnt lgkmcnt(0)
	v_lshl_add_u64 v[32:33], s[94:95], 0, v[26:27]
	v_cndmask_b32_e32 v0, v43, v44, vcc
	v_and_b32_e32 v0, v0, v49
	v_cndmask_b32_e32 v1, v45, v46, vcc
	v_cmp_gt_i32_e64 s[12:13], v49, v0
	v_add_u32_e32 v0, v0, v1
	v_cmp_lt_i32_e64 s[14:15], v49, v0
	v_cndmask_b32_e64 v1, 0, -1, s[12:13]
	v_cndmask_b32_e64 v0, 0, v47, s[12:13]
	v_lshl_add_u64 v[0:1], v[26:27], 0, v[0:1]
	v_cndmask_b32_e64 v2, 0, v48, s[14:15]
	v_add_co_u32_e32 v38, vcc, s68, v32
	v_lshl_add_u64 v[0:1], s[94:95], 0, v[0:1]
	v_lshl_add_u64 v[36:37], v[26:27], 0, v[2:3]
	v_addc_co_u32_e32 v39, vcc, 0, v33, vcc
	v_lshl_add_u64 v[50:51], s[94:95], 0, v[36:37]
	v_add_co_u32_e32 v36, vcc, s68, v0
	v_lshl_add_u64 v[34:35], s[94:95], 0, v[28:29]
	s_nop 0
	v_addc_co_u32_e32 v37, vcc, 0, v1, vcc
	v_add_co_u32_e32 v0, vcc, s68, v50
	global_load_ushort v95, v[38:39], off offset:128
	global_load_ushort v97, v[36:37], off offset:128
	v_addc_co_u32_e32 v1, vcc, 0, v51, vcc
	v_add_co_u32_e32 v34, vcc, s1, v34
	global_load_ushort v98, v[0:1], off offset:128
	global_load_ushort v96, v[38:39], off offset:1152
	global_load_ushort v94, v[36:37], off offset:1152
	global_load_ushort v93, v[0:1], off offset:1152
	v_addc_co_u32_e32 v35, vcc, 0, v35, vcc
	global_load_ushort v92, v[34:35], off offset:128
	global_load_ushort v91, v[38:39], off offset:256
	global_load_ushort v90, v[36:37], off offset:256
	global_load_ushort v89, v[0:1], off offset:256
	global_load_ushort v88, v[38:39], off offset:1280
	global_load_ushort v87, v[36:37], off offset:1280
	global_load_ushort v86, v[0:1], off offset:1280
	global_load_ushort v85, v[34:35], off offset:256
	global_load_ushort v84, v[38:39], off offset:384
	global_load_ushort v83, v[36:37], off offset:384
	global_load_ushort v82, v[0:1], off offset:384
	global_load_ushort v81, v[38:39], off offset:1408
	global_load_ushort v80, v[36:37], off offset:1408
	global_load_ushort v79, v[0:1], off offset:1408
	global_load_ushort v78, v[34:35], off offset:384
	global_load_ushort v77, v[38:39], off offset:512
	global_load_ushort v76, v[36:37], off offset:512
	global_load_ushort v75, v[0:1], off offset:512
	global_load_ushort v74, v[38:39], off offset:1536
	global_load_ushort v73, v[36:37], off offset:1536
	global_load_ushort v72, v[0:1], off offset:1536
	global_load_ushort v71, v[34:35], off offset:512
	global_load_ushort v70, v[38:39], off offset:640
	global_load_ushort v69, v[36:37], off offset:640
	global_load_ushort v68, v[0:1], off offset:640
	global_load_ushort v67, v[38:39], off offset:1664
	global_load_ushort v66, v[36:37], off offset:1664
	global_load_ushort v65, v[0:1], off offset:1664
	global_load_ushort v64, v[34:35], off offset:640
	global_load_ushort v63, v[38:39], off offset:768
	global_load_ushort v62, v[36:37], off offset:768
	global_load_ushort v61, v[0:1], off offset:768
	global_load_ushort v60, v[38:39], off offset:1792
	global_load_ushort v59, v[36:37], off offset:1792
	global_load_ushort v58, v[0:1], off offset:1792
	global_load_ushort v57, v[34:35], off offset:768
	global_load_ushort v56, v[38:39], off offset:896
	global_load_ushort v55, v[36:37], off offset:896
	global_load_ushort v54, v[0:1], off offset:896
	global_load_ushort v53, v[38:39], off offset:1920
	global_load_ushort v52, v[36:37], off offset:1920
	global_load_ushort v51, v[0:1], off offset:1920
	global_load_ushort v50, v[34:35], off offset:896
	global_load_ushort v2, v[38:39], off
	v_mov_b32_e32 v99, v110
	global_load_ushort v100, v[36:37], off
	v_mov_b32_e32 v101, v111
	global_load_ushort v102, v[0:1], off
	v_lshl_add_u64 v[32:33], s[94:95], 0, v[30:31]
	global_load_ushort v38, v[38:39], off offset:1024
	s_nop 0
	v_mov_b32_e32 v39, v112
	s_nop 0
	global_load_ushort v36, v[36:37], off offset:1024
	s_nop 0
	v_mov_b32_e32 v37, v113
	s_nop 0
	global_load_ushort v0, v[0:1], off offset:1024
	s_waitcnt vmcnt(5)
	v_lshlrev_b32_e32 v2, 16, v2
	s_waitcnt vmcnt(4)
	v_lshlrev_b32_e32 v100, 16, v100
	v_cndmask_b32_e64 v100, 0, v100, s[12:13]
	s_waitcnt vmcnt(3)
	v_lshlrev_b32_e32 v102, 16, v102
	s_waitcnt vmcnt(2)
	v_lshlrev_b32_e32 v38, 16, v38
	s_waitcnt vmcnt(1)
	v_lshlrev_b32_e32 v36, 16, v36
	v_cndmask_b32_e64 v36, 0, v36, s[12:13]
	s_waitcnt vmcnt(0)
	v_lshlrev_b32_e32 v0, 16, v0
	v_sub_f32_e32 v36, v36, v38
	v_cndmask_b32_e64 v0, 0, v0, s[14:15]
	v_sub_f32_e32 v0, v0, v38
	v_fmac_f32_e32 v38, v36, v39
	v_fmac_f32_e32 v38, v0, v37
	global_load_ushort v0, v[34:35], off
	v_mov_b32_e32 v36, v114
	v_sub_f32_e32 v100, v100, v2
	v_cndmask_b32_e64 v102, 0, v102, s[14:15]
	v_sub_f32_e32 v102, v102, v2
	v_fmac_f32_e32 v2, v100, v99
	v_fmac_f32_e32 v2, v102, v101
	s_waitcnt vmcnt(0)
	v_lshlrev_b32_e32 v1, 16, v0
	v_mov_b32_e32 v0, v115
	v_mul_f32_e32 v34, v0, v38
	v_mul_f32_e32 v0, v34, v34
	s_nop 1
	v_mov_b32_dpp v0, v0 row_ror:8 row_mask:0xf bank_mask:0xf bound_ctrl:1
	v_fmac_f32_e32 v0, v34, v34
	s_nop 1
	v_add_f32_dpp v0, v0, v0 row_ror:4 row_mask:0xf bank_mask:0xf bound_ctrl:1
	s_nop 1
	v_add_f32_dpp v0, v0, v0 row_ror:2 row_mask:0xf bank_mask:0xf bound_ctrl:1
	s_nop 1
	v_add_f32_dpp v0, v0, v0 row_ror:1 row_mask:0xf bank_mask:0xf bound_ctrl:1
	s_nop 0
	v_readlane_b32 s72, v0, 16
	v_readlane_b32 s87, v0, 48
	v_readlane_b32 s1, v0, 0
	v_readlane_b32 s86, v0, 32
	v_mov_b32_e32 v0, s72
	v_mov_b32_e32 v35, s87
	v_add_f32_e32 v0, s1, v0
	v_add_f32_e32 v35, s86, v35
	v_add_f32_e32 v0, v0, v35
	v_max_f32_e32 v0, 0x179abe15, v0
	v_rsq_f32_e32 v0, v0
	v_add_f32_e32 v35, -1.0, v1
	v_fma_f32 v35, v35, v36, 1.0
	v_mul_f32_e32 v35, v38, v35
	v_mul_f32_e32 v34, v34, v0
	v_mul_f32_e32 v1, v34, v1
	v_mul_f32_e32 v34, v2, v1
	s_nop 1
	v_mov_b32_dpp v34, v34 row_ror:8 row_mask:0xf bank_mask:0xf bound_ctrl:1
	v_fmac_f32_e32 v34, v2, v1
	s_nop 1
	v_add_f32_dpp v1, v34, v34 row_ror:4 row_mask:0xf bank_mask:0xf bound_ctrl:1
	s_nop 1
	v_add_f32_dpp v1, v1, v1 row_ror:2 row_mask:0xf bank_mask:0xf bound_ctrl:1
	s_nop 1
	v_add_f32_dpp v1, v1, v1 row_ror:1 row_mask:0xf bank_mask:0xf bound_ctrl:1
	s_nop 0
	v_readlane_b32 s86, v1, 0
	v_readlane_b32 s72, v1, 16
	v_readlane_b32 s88, v1, 32
	v_readlane_b32 s1, v1, 48
	v_mul_f32_e32 v1, v2, v35
	v_mov_b32_e32 v2, v116
	v_mul_f32_e32 v34, v1, v2
	s_nop 1
	v_mov_b32_dpp v34, v34 row_ror:8 row_mask:0xf bank_mask:0xf bound_ctrl:1
	v_fmac_f32_e32 v34, v1, v2
	s_nop 1
	v_add_f32_dpp v1, v34, v34 row_ror:4 row_mask:0xf bank_mask:0xf bound_ctrl:1
	s_nop 1
	v_add_f32_dpp v1, v1, v1 row_ror:2 row_mask:0xf bank_mask:0xf bound_ctrl:1
	s_nop 1
	v_add_f32_dpp v1, v1, v1 row_ror:1 row_mask:0xf bank_mask:0xf bound_ctrl:1
	s_nop 0
	v_readlane_b32 s87, v1, 0
	v_readlane_b32 s93, v1, 16
	v_readlane_b32 s89, v1, 32
	v_readlane_b32 s92, v1, 48
	s_and_saveexec_b64 s[90:91], s[8:9]
	s_cbranch_execz .LBB0_1852
; DEV float bf2f(bf16_t b) { return __uint_as_float(((unsigned)b) << 16); }
; DEV void phase_rw_pre(const Params& p) {
;     ...
;     for (int h = 0; h < 8; ++h) {
;       const int hc = h * 64 + lane;
;       float x = bf2f(raw[h][0]);
;       const float r = x + p.in[14][hc] * ((hp ? bf2f(raw[h][1]) : 0.f) - x) + p.in[15][hc] * ((hn ? bf2f(raw[h][2]) : 0.f) - x);
;       x = bf2f(raw[h][3]);
;       const float kr = x + p.in[14][512 + hc] * ((hp ? bf2f(raw[h][4]) : 0.f) - x) + p.in[15][512 + hc] * ((hn ? bf2f(raw[h][5]) : 0.f) - x);
;       const float a = bf2f(raw[h][6]);
;       const float kkr = kr * p.in[23][hc];
;       const float inv = rsqrtf(fmaxf(wave_sum_dpp(kkr * kkr), 1e-24f));
;       const float kk = kkr * inv;
;       const float k2 = kr * (1.f + (a - 1.f) * p.in[24][hc]);
;       const float kar = wave_sum_dpp(kk * a * r);
;       const float bo = wave_sum_dpp(r * k2 * p.in[25][hc]);
;       if (lane == 0) *(float4*)(scal + ((size_t)t * 8 + h) * 4) = make_float4(inv, kar, bo, 0.f);
	v_mov_b32_e32 v34, s72
	v_mov_b32_e32 v35, s93
	v_mov_b32_e32 v36, s1
	v_mov_b32_e32 v37, s92
	v_pk_add_f32 v[34:35], s[86:87], v[34:35]
	v_pk_add_f32 v[36:37], s[88:89], v[36:37]
	s_nop 0
	v_pk_add_f32 v[34:35], v[34:35], v[36:37]
	s_nop 0
	v_mov_b32_e32 v1, v34
	v_add_co_u32_e32 v34, vcc, 0x1c500000, v32
	v_mov_b32_e32 v2, v35
	s_nop 0
	v_addc_co_u32_e32 v35, vcc, 0, v33, vcc
	global_store_dwordx4 v[34:35], v[0:3], off
.LBB0_1852:
	s_or_b64 exec, exec, s[90:91]
	s_nop 0
	v_mov_b32_e32 v0, v117
	v_lshlrev_b32_e32 v2, 16, v97
	v_mov_b32_e32 v34, v118
	v_lshlrev_b32_e32 v1, 16, v95
	v_cndmask_b32_e64 v2, 0, v2, s[12:13]
	v_lshlrev_b32_e32 v35, 16, v98
	v_sub_f32_e32 v2, v2, v1
	v_cndmask_b32_e64 v35, 0, v35, s[14:15]
	v_sub_f32_e32 v35, v35, v1
	v_lshlrev_b32_e32 v36, 16, v93
	v_cndmask_b32_e64 v36, 0, v36, s[14:15]
	v_mov_b32_e32 v37, v119
	s_waitcnt vmcnt(0)
	v_fmac_f32_e32 v1, v2, v0
	v_mov_b32_e32 v0, v120
	v_fmac_f32_e32 v1, v35, v34
	v_lshlrev_b32_e32 v34, 16, v94
	v_lshlrev_b32_e32 v2, 16, v96
	v_cndmask_b32_e64 v34, 0, v34, s[12:13]
	v_sub_f32_e32 v34, v34, v2
	v_mov_b32_e32 v35, v121
	v_sub_f32_e32 v36, v36, v2
	v_fmac_f32_e32 v2, v34, v0
	v_mov_b32_e32 v0, v122
	v_lshlrev_b32_e32 v34, 16, v92
	v_fmac_f32_e32 v2, v36, v35
	v_mul_f32_e32 v35, v0, v2
	v_mul_f32_e32 v0, v35, v35
	s_nop 1
	v_mov_b32_dpp v0, v0 row_ror:8 row_mask:0xf bank_mask:0xf bound_ctrl:1
	v_fmac_f32_e32 v0, v35, v35
	s_nop 1
	v_add_f32_dpp v0, v0, v0 row_ror:4 row_mask:0xf bank_mask:0xf bound_ctrl:1
	s_nop 1
	v_add_f32_dpp v0, v0, v0 row_ror:2 row_mask:0xf bank_mask:0xf bound_ctrl:1
	s_nop 1
	v_add_f32_dpp v0, v0, v0 row_ror:1 row_mask:0xf bank_mask:0xf bound_ctrl:1
	s_nop 0
	v_readlane_b32 s72, v0, 16
	v_readlane_b32 s87, v0, 48
	v_readlane_b32 s1, v0, 0
	v_readlane_b32 s86, v0, 32
	v_mov_b32_e32 v0, s72
	v_mov_b32_e32 v36, s87
	v_add_f32_e32 v0, s1, v0
	v_add_f32_e32 v36, s86, v36
	v_add_f32_e32 v0, v0, v36
	v_max_f32_e32 v0, 0x179abe15, v0
	v_rsq_f32_e32 v0, v0
	v_add_f32_e32 v36, -1.0, v34
	v_fma_f32 v36, v36, v37, 1.0
	v_mul_f32_e32 v2, v2, v36
	v_mul_f32_e32 v35, v35, v0
	v_mul_f32_e32 v34, v35, v34
	v_mul_f32_e32 v35, v1, v34
	s_nop 1
	v_mov_b32_dpp v35, v35 row_ror:8 row_mask:0xf bank_mask:0xf bound_ctrl:1
	v_fmac_f32_e32 v35, v1, v34
	v_mul_f32_e32 v1, v1, v2
	v_mov_b32_e32 v2, v123
	v_add_f32_dpp v34, v35, v35 row_ror:4 row_mask:0xf bank_mask:0xf bound_ctrl:1
	s_nop 1
	v_add_f32_dpp v34, v34, v34 row_ror:2 row_mask:0xf bank_mask:0xf bound_ctrl:1
	s_nop 1
	v_add_f32_dpp v34, v34, v34 row_ror:1 row_mask:0xf bank_mask:0xf bound_ctrl:1
	s_nop 0
	v_readlane_b32 s86, v34, 0
	v_readlane_b32 s72, v34, 16
	v_readlane_b32 s88, v34, 32
	v_readlane_b32 s1, v34, 48
	v_mul_f32_e32 v34, v1, v2
	s_nop 1
	v_mov_b32_dpp v34, v34 row_ror:8 row_mask:0xf bank_mask:0xf bound_ctrl:1
	v_fmac_f32_e32 v34, v1, v2
	s_nop 1
	v_add_f32_dpp v1, v34, v34 row_ror:4 row_mask:0xf bank_mask:0xf bound_ctrl:1
	s_nop 1
	v_add_f32_dpp v1, v1, v1 row_ror:2 row_mask:0xf bank_mask:0xf bound_ctrl:1
	s_nop 1
	v_add_f32_dpp v1, v1, v1 row_ror:1 row_mask:0xf bank_mask:0xf bound_ctrl:1
	s_nop 0
	v_readlane_b32 s87, v1, 0
	v_readlane_b32 s92, v1, 16
	v_readlane_b32 s89, v1, 32
	v_readlane_b32 s93, v1, 48
	s_and_saveexec_b64 s[90:91], s[8:9]
	s_cbranch_execz .LBB0_1854
	v_mov_b32_e32 v34, s72
	v_mov_b32_e32 v35, s92
	v_mov_b32_e32 v36, s1
	v_mov_b32_e32 v37, s93
	v_pk_add_f32 v[34:35], s[86:87], v[34:35]
	v_pk_add_f32 v[36:37], s[88:89], v[36:37]
	s_nop 0
	v_pk_add_f32 v[34:35], v[34:35], v[36:37]
	s_nop 0
	v_mov_b32_e32 v1, v34
	v_add_co_u32_e32 v34, vcc, 0x1c500000, v32
	v_mov_b32_e32 v2, v35
	s_nop 0
	v_addc_co_u32_e32 v35, vcc, 0, v33, vcc
	global_store_dwordx4 v[34:35], v[0:3], off offset:16
.LBB0_1854:
	s_or_b64 exec, exec, s[90:91]
	s_nop 0
	v_mov_b32_e32 v0, v124
	v_lshlrev_b32_e32 v2, 16, v90
	v_mov_b32_e32 v34, v125
	v_lshlrev_b32_e32 v1, 16, v91
	v_cndmask_b32_e64 v2, 0, v2, s[12:13]
	v_lshlrev_b32_e32 v35, 16, v89
	v_sub_f32_e32 v2, v2, v1
	v_cndmask_b32_e64 v35, 0, v35, s[14:15]
	v_sub_f32_e32 v35, v35, v1
	v_lshlrev_b32_e32 v36, 16, v86
	v_cndmask_b32_e64 v36, 0, v36, s[14:15]
	v_mov_b32_e32 v37, v126
	s_waitcnt vmcnt(0)
	v_fmac_f32_e32 v1, v2, v0
	v_mov_b32_e32 v0, v127
	v_fmac_f32_e32 v1, v35, v34
	v_lshlrev_b32_e32 v34, 16, v87
	v_lshlrev_b32_e32 v2, 16, v88
	v_cndmask_b32_e64 v34, 0, v34, s[12:13]
	v_sub_f32_e32 v34, v34, v2
	v_mov_b32_e32 v35, v128
	v_sub_f32_e32 v36, v36, v2
	v_fmac_f32_e32 v2, v34, v0
	v_mov_b32_e32 v0, v129
	v_lshlrev_b32_e32 v34, 16, v85
	v_fmac_f32_e32 v2, v36, v35
	v_mul_f32_e32 v35, v0, v2
	v_mul_f32_e32 v0, v35, v35
	s_nop 1
	v_mov_b32_dpp v0, v0 row_ror:8 row_mask:0xf bank_mask:0xf bound_ctrl:1
	v_fmac_f32_e32 v0, v35, v35
	s_nop 1
	v_add_f32_dpp v0, v0, v0 row_ror:4 row_mask:0xf bank_mask:0xf bound_ctrl:1
	s_nop 1
	v_add_f32_dpp v0, v0, v0 row_ror:2 row_mask:0xf bank_mask:0xf bound_ctrl:1
	s_nop 1
	v_add_f32_dpp v0, v0, v0 row_ror:1 row_mask:0xf bank_mask:0xf bound_ctrl:1
	s_nop 0
	v_readlane_b32 s72, v0, 16
	v_readlane_b32 s87, v0, 48
	v_readlane_b32 s1, v0, 0
	v_readlane_b32 s86, v0, 32
	v_mov_b32_e32 v0, s72
	v_mov_b32_e32 v36, s87
	v_add_f32_e32 v0, s1, v0
	v_add_f32_e32 v36, s86, v36
	v_add_f32_e32 v0, v0, v36
	v_max_f32_e32 v0, 0x179abe15, v0
	v_rsq_f32_e32 v0, v0
	v_add_f32_e32 v36, -1.0, v34
	v_fma_f32 v36, v36, v37, 1.0
	v_mul_f32_e32 v2, v2, v36
	v_mul_f32_e32 v35, v35, v0
	v_mul_f32_e32 v34, v35, v34
	v_mul_f32_e32 v35, v1, v34
	s_nop 1
	v_mov_b32_dpp v35, v35 row_ror:8 row_mask:0xf bank_mask:0xf bound_ctrl:1
	v_fmac_f32_e32 v35, v1, v34
	v_mul_f32_e32 v1, v1, v2
	v_mov_b32_e32 v2, v130
	v_add_f32_dpp v34, v35, v35 row_ror:4 row_mask:0xf bank_mask:0xf bound_ctrl:1
	s_nop 1
	v_add_f32_dpp v34, v34, v34 row_ror:2 row_mask:0xf bank_mask:0xf bound_ctrl:1
	s_nop 1
	v_add_f32_dpp v34, v34, v34 row_ror:1 row_mask:0xf bank_mask:0xf bound_ctrl:1
	s_nop 0
	v_readlane_b32 s86, v34, 0
	v_readlane_b32 s72, v34, 16
	v_readlane_b32 s88, v34, 32
	v_readlane_b32 s1, v34, 48
	v_mul_f32_e32 v34, v1, v2
	s_nop 1
	v_mov_b32_dpp v34, v34 row_ror:8 row_mask:0xf bank_mask:0xf bound_ctrl:1
	v_fmac_f32_e32 v34, v1, v2
	s_nop 1
	v_add_f32_dpp v1, v34, v34 row_ror:4 row_mask:0xf bank_mask:0xf bound_ctrl:1
	s_nop 1
	v_add_f32_dpp v1, v1, v1 row_ror:2 row_mask:0xf bank_mask:0xf bound_ctrl:1
	s_nop 1
	v_add_f32_dpp v1, v1, v1 row_ror:1 row_mask:0xf bank_mask:0xf bound_ctrl:1
	s_nop 0
	v_readlane_b32 s87, v1, 0
	v_readlane_b32 s92, v1, 16
	v_readlane_b32 s89, v1, 32
	v_readlane_b32 s93, v1, 48
	s_and_saveexec_b64 s[90:91], s[8:9]
	s_cbranch_execz .LBB0_1856
	v_mov_b32_e32 v34, s72
	v_mov_b32_e32 v35, s92
	v_mov_b32_e32 v36, s1
	v_mov_b32_e32 v37, s93
	v_pk_add_f32 v[34:35], s[86:87], v[34:35]
	v_pk_add_f32 v[36:37], s[88:89], v[36:37]
	s_nop 0
	v_pk_add_f32 v[34:35], v[34:35], v[36:37]
	s_nop 0
	v_mov_b32_e32 v1, v34
	v_add_co_u32_e32 v34, vcc, 0x1c500000, v32
	v_mov_b32_e32 v2, v35
	s_nop 0
	v_addc_co_u32_e32 v35, vcc, 0, v33, vcc
	global_store_dwordx4 v[34:35], v[0:3], off offset:32
; DEV float bf2f(bf16_t b) { return __uint_as_float(((unsigned)b) << 16); }
; DEV void phase_rw_pre(const Params& p) {
;     ...
;     for (int h = 0; h < 8; ++h) {
;       const int hc = h * 64 + lane;
;       float x = bf2f(raw[h][0]);
;       const float r = x + p.in[14][hc] * ((hp ? bf2f(raw[h][1]) : 0.f) - x) + p.in[15][hc] * ((hn ? bf2f(raw[h][2]) : 0.f) - x);
;       x = bf2f(raw[h][3]);
;       const float kr = x + p.in[14][512 + hc] * ((hp ? bf2f(raw[h][4]) : 0.f) - x) + p.in[15][512 + hc] * ((hn ? bf2f(raw[h][5]) : 0.f) - x);
;       const float a = bf2f(raw[h][6]);
;       const float kkr = kr * p.in[23][hc];
;       const float inv = rsqrtf(fmaxf(wave_sum_dpp(kkr * kkr), 1e-24f));
;       const float kk = kkr * inv;
;       const float k2 = kr * (1.f + (a - 1.f) * p.in[24][hc]);
;       const float kar = wave_sum_dpp(kk * a * r);
;       const float bo = wave_sum_dpp(r * k2 * p.in[25][hc]);
;       if (lane == 0) *(float4*)(scal + ((size_t)t * 8 + h) * 4) = make_float4(inv, kar, bo, 0.f);
.LBB0_1856:
	s_or_b64 exec, exec, s[90:91]
	s_nop 0
	v_mov_b32_e32 v0, v131
	v_lshlrev_b32_e32 v2, 16, v83
	v_mov_b32_e32 v34, v132
	v_lshlrev_b32_e32 v1, 16, v84
	v_cndmask_b32_e64 v2, 0, v2, s[12:13]
	v_lshlrev_b32_e32 v35, 16, v82
	v_sub_f32_e32 v2, v2, v1
	v_cndmask_b32_e64 v35, 0, v35, s[14:15]
	v_sub_f32_e32 v35, v35, v1
	v_lshlrev_b32_e32 v36, 16, v79
	v_cndmask_b32_e64 v36, 0, v36, s[14:15]
	v_mov_b32_e32 v37, v133
	s_waitcnt vmcnt(0)
	v_fmac_f32_e32 v1, v2, v0
	v_mov_b32_e32 v0, v134
	v_fmac_f32_e32 v1, v35, v34
	v_lshlrev_b32_e32 v34, 16, v80
	v_lshlrev_b32_e32 v2, 16, v81
	v_cndmask_b32_e64 v34, 0, v34, s[12:13]
	v_sub_f32_e32 v34, v34, v2
	v_mov_b32_e32 v35, v136
	v_sub_f32_e32 v36, v36, v2
	v_fmac_f32_e32 v2, v34, v0
	v_mov_b32_e32 v0, v137
	v_lshlrev_b32_e32 v34, 16, v78
	v_fmac_f32_e32 v2, v36, v35
	v_mul_f32_e32 v35, v0, v2
	v_mul_f32_e32 v0, v35, v35
	s_nop 1
	v_mov_b32_dpp v0, v0 row_ror:8 row_mask:0xf bank_mask:0xf bound_ctrl:1
	v_fmac_f32_e32 v0, v35, v35
	s_nop 1
	v_add_f32_dpp v0, v0, v0 row_ror:4 row_mask:0xf bank_mask:0xf bound_ctrl:1
	s_nop 1
	v_add_f32_dpp v0, v0, v0 row_ror:2 row_mask:0xf bank_mask:0xf bound_ctrl:1
	s_nop 1
	v_add_f32_dpp v0, v0, v0 row_ror:1 row_mask:0xf bank_mask:0xf bound_ctrl:1
	s_nop 0
	v_readlane_b32 s72, v0, 16
	v_readlane_b32 s87, v0, 48
	v_readlane_b32 s1, v0, 0
	v_readlane_b32 s86, v0, 32
	v_mov_b32_e32 v0, s72
	v_mov_b32_e32 v36, s87
	v_add_f32_e32 v0, s1, v0
	v_add_f32_e32 v36, s86, v36
	v_add_f32_e32 v0, v0, v36
	v_max_f32_e32 v0, 0x179abe15, v0
	v_rsq_f32_e32 v0, v0
	v_add_f32_e32 v36, -1.0, v34
	v_fma_f32 v36, v36, v37, 1.0
	v_mul_f32_e32 v2, v2, v36
	v_mul_f32_e32 v35, v35, v0
	v_mul_f32_e32 v34, v35, v34
	v_mul_f32_e32 v35, v1, v34
	s_nop 1
	v_mov_b32_dpp v35, v35 row_ror:8 row_mask:0xf bank_mask:0xf bound_ctrl:1
	v_fmac_f32_e32 v35, v1, v34
	v_mul_f32_e32 v1, v1, v2
	v_mov_b32_e32 v2, v138
	v_add_f32_dpp v34, v35, v35 row_ror:4 row_mask:0xf bank_mask:0xf bound_ctrl:1
	s_nop 1
	v_add_f32_dpp v34, v34, v34 row_ror:2 row_mask:0xf bank_mask:0xf bound_ctrl:1
	s_nop 1
	v_add_f32_dpp v34, v34, v34 row_ror:1 row_mask:0xf bank_mask:0xf bound_ctrl:1
	s_nop 0
	v_readlane_b32 s86, v34, 0
	v_readlane_b32 s72, v34, 16
	v_readlane_b32 s88, v34, 32
	v_readlane_b32 s1, v34, 48
	v_mul_f32_e32 v34, v1, v2
	s_nop 1
	v_mov_b32_dpp v34, v34 row_ror:8 row_mask:0xf bank_mask:0xf bound_ctrl:1
	v_fmac_f32_e32 v34, v1, v2
	s_nop 1
	v_add_f32_dpp v1, v34, v34 row_ror:4 row_mask:0xf bank_mask:0xf bound_ctrl:1
	s_nop 1
	v_add_f32_dpp v1, v1, v1 row_ror:2 row_mask:0xf bank_mask:0xf bound_ctrl:1
	s_nop 1
	v_add_f32_dpp v1, v1, v1 row_ror:1 row_mask:0xf bank_mask:0xf bound_ctrl:1
	s_nop 0
	v_readlane_b32 s87, v1, 0
	v_readlane_b32 s92, v1, 16
	v_readlane_b32 s89, v1, 32
	v_readlane_b32 s93, v1, 48
	s_and_saveexec_b64 s[90:91], s[8:9]
	s_cbranch_execz .LBB0_1858
	v_mov_b32_e32 v34, s72
	v_mov_b32_e32 v35, s92
	v_mov_b32_e32 v36, s1
	v_mov_b32_e32 v37, s93
	v_pk_add_f32 v[34:35], s[86:87], v[34:35]
	v_pk_add_f32 v[36:37], s[88:89], v[36:37]
	s_nop 0
	v_pk_add_f32 v[34:35], v[34:35], v[36:37]
	s_nop 0
	v_mov_b32_e32 v1, v34
	v_add_co_u32_e32 v34, vcc, 0x1c500000, v32
	v_mov_b32_e32 v2, v35
	s_nop 0
	v_addc_co_u32_e32 v35, vcc, 0, v33, vcc
	global_store_dwordx4 v[34:35], v[0:3], off offset:48
.LBB0_1858:
	s_or_b64 exec, exec, s[90:91]
	s_nop 0
	v_mov_b32_e32 v0, v139
	v_lshlrev_b32_e32 v2, 16, v76
	v_mov_b32_e32 v34, v142
	v_lshlrev_b32_e32 v1, 16, v77
	v_cndmask_b32_e64 v2, 0, v2, s[12:13]
	v_lshlrev_b32_e32 v35, 16, v75
	v_sub_f32_e32 v2, v2, v1
	v_cndmask_b32_e64 v35, 0, v35, s[14:15]
	v_sub_f32_e32 v35, v35, v1
	v_lshlrev_b32_e32 v36, 16, v72
	v_cndmask_b32_e64 v36, 0, v36, s[14:15]
	v_mov_b32_e32 v37, v143
	s_waitcnt vmcnt(0)
	v_fmac_f32_e32 v1, v2, v0
	v_mov_b32_e32 v0, v144
	v_fmac_f32_e32 v1, v35, v34
	v_lshlrev_b32_e32 v34, 16, v73
	v_lshlrev_b32_e32 v2, 16, v74
	v_cndmask_b32_e64 v34, 0, v34, s[12:13]
	v_sub_f32_e32 v34, v34, v2
	v_mov_b32_e32 v35, v145
	v_sub_f32_e32 v36, v36, v2
	v_fmac_f32_e32 v2, v34, v0
	v_mov_b32_e32 v0, v146
	v_lshlrev_b32_e32 v34, 16, v71
	v_fmac_f32_e32 v2, v36, v35
	v_mul_f32_e32 v35, v0, v2
	v_mul_f32_e32 v0, v35, v35
	s_nop 1
	v_mov_b32_dpp v0, v0 row_ror:8 row_mask:0xf bank_mask:0xf bound_ctrl:1
	v_fmac_f32_e32 v0, v35, v35
	s_nop 1
	v_add_f32_dpp v0, v0, v0 row_ror:4 row_mask:0xf bank_mask:0xf bound_ctrl:1
	s_nop 1
	v_add_f32_dpp v0, v0, v0 row_ror:2 row_mask:0xf bank_mask:0xf bound_ctrl:1
	s_nop 1
	v_add_f32_dpp v0, v0, v0 row_ror:1 row_mask:0xf bank_mask:0xf bound_ctrl:1
	s_nop 0
	v_readlane_b32 s72, v0, 16
	v_readlane_b32 s87, v0, 48
	v_readlane_b32 s1, v0, 0
	v_readlane_b32 s86, v0, 32
	v_mov_b32_e32 v0, s72
	v_mov_b32_e32 v36, s87
	v_add_f32_e32 v0, s1, v0
	v_add_f32_e32 v36, s86, v36
	v_add_f32_e32 v0, v0, v36
	v_max_f32_e32 v0, 0x179abe15, v0
	v_rsq_f32_e32 v0, v0
	v_add_f32_e32 v36, -1.0, v34
	v_fma_f32 v36, v36, v37, 1.0
	v_mul_f32_e32 v2, v2, v36
	v_mul_f32_e32 v35, v35, v0
	v_mul_f32_e32 v34, v35, v34
	v_mul_f32_e32 v35, v1, v34
	s_nop 1
	v_mov_b32_dpp v35, v35 row_ror:8 row_mask:0xf bank_mask:0xf bound_ctrl:1
	v_fmac_f32_e32 v35, v1, v34
	v_mul_f32_e32 v1, v1, v2
	v_mov_b32_e32 v2, v147
	v_add_f32_dpp v34, v35, v35 row_ror:4 row_mask:0xf bank_mask:0xf bound_ctrl:1
	s_nop 1
	v_add_f32_dpp v34, v34, v34 row_ror:2 row_mask:0xf bank_mask:0xf bound_ctrl:1
	s_nop 1
	v_add_f32_dpp v34, v34, v34 row_ror:1 row_mask:0xf bank_mask:0xf bound_ctrl:1
	s_nop 0
	v_readlane_b32 s86, v34, 0
	v_readlane_b32 s72, v34, 16
	v_readlane_b32 s88, v34, 32
	v_readlane_b32 s1, v34, 48
	v_mul_f32_e32 v34, v1, v2
	s_nop 1
	v_mov_b32_dpp v34, v34 row_ror:8 row_mask:0xf bank_mask:0xf bound_ctrl:1
	v_fmac_f32_e32 v34, v1, v2
	s_nop 1
	v_add_f32_dpp v1, v34, v34 row_ror:4 row_mask:0xf bank_mask:0xf bound_ctrl:1
	s_nop 1
	v_add_f32_dpp v1, v1, v1 row_ror:2 row_mask:0xf bank_mask:0xf bound_ctrl:1
	s_nop 1
	v_add_f32_dpp v1, v1, v1 row_ror:1 row_mask:0xf bank_mask:0xf bound_ctrl:1
	s_nop 0
	v_readlane_b32 s87, v1, 0
	v_readlane_b32 s92, v1, 16
	v_readlane_b32 s89, v1, 32
	v_readlane_b32 s93, v1, 48
	s_and_saveexec_b64 s[90:91], s[8:9]
	s_cbranch_execz .LBB0_1860
	v_mov_b32_e32 v34, s72
	v_mov_b32_e32 v35, s92
	v_mov_b32_e32 v36, s1
	v_mov_b32_e32 v37, s93
	v_pk_add_f32 v[34:35], s[86:87], v[34:35]
	v_pk_add_f32 v[36:37], s[88:89], v[36:37]
	s_nop 0
	v_pk_add_f32 v[34:35], v[34:35], v[36:37]
	s_nop 0
	v_mov_b32_e32 v1, v34
	v_add_co_u32_e32 v34, vcc, 0x1c500000, v32
	v_mov_b32_e32 v2, v35
	s_nop 0
	v_addc_co_u32_e32 v35, vcc, 0, v33, vcc
	global_store_dwordx4 v[34:35], v[0:3], off offset:64
; DEV float bf2f(bf16_t b) { return __uint_as_float(((unsigned)b) << 16); }
; DEV void phase_rw_pre(const Params& p) {
;     ...
;     for (int h = 0; h < 8; ++h) {
;       const int hc = h * 64 + lane;
;       float x = bf2f(raw[h][0]);
;       const float r = x + p.in[14][hc] * ((hp ? bf2f(raw[h][1]) : 0.f) - x) + p.in[15][hc] * ((hn ? bf2f(raw[h][2]) : 0.f) - x);
;       x = bf2f(raw[h][3]);
;       const float kr = x + p.in[14][512 + hc] * ((hp ? bf2f(raw[h][4]) : 0.f) - x) + p.in[15][512 + hc] * ((hn ? bf2f(raw[h][5]) : 0.f) - x);
;       const float a = bf2f(raw[h][6]);
;       const float kkr = kr * p.in[23][hc];
;       const float inv = rsqrtf(fmaxf(wave_sum_dpp(kkr * kkr), 1e-24f));
;       const float kk = kkr * inv;
;       const float k2 = kr * (1.f + (a - 1.f) * p.in[24][hc]);
;       const float kar = wave_sum_dpp(kk * a * r);
;       const float bo = wave_sum_dpp(r * k2 * p.in[25][hc]);
;       if (lane == 0) *(float4*)(scal + ((size_t)t * 8 + h) * 4) = make_float4(inv, kar, bo, 0.f);
.LBB0_1860:
	s_or_b64 exec, exec, s[90:91]
	s_nop 0
	v_mov_b32_e32 v0, v148
	v_lshlrev_b32_e32 v2, 16, v69
	v_mov_b32_e32 v34, v149
	v_lshlrev_b32_e32 v1, 16, v70
	v_cndmask_b32_e64 v2, 0, v2, s[12:13]
	v_lshlrev_b32_e32 v35, 16, v68
	v_sub_f32_e32 v2, v2, v1
	v_cndmask_b32_e64 v35, 0, v35, s[14:15]
	v_sub_f32_e32 v35, v35, v1
	v_lshlrev_b32_e32 v36, 16, v65
	v_cndmask_b32_e64 v36, 0, v36, s[14:15]
	v_mov_b32_e32 v37, v150
	s_waitcnt vmcnt(0)
	v_fmac_f32_e32 v1, v2, v0
	v_mov_b32_e32 v0, v151
	v_fmac_f32_e32 v1, v35, v34
	v_lshlrev_b32_e32 v34, 16, v66
	v_lshlrev_b32_e32 v2, 16, v67
	v_cndmask_b32_e64 v34, 0, v34, s[12:13]
	v_sub_f32_e32 v34, v34, v2
	v_mov_b32_e32 v35, v152
	v_sub_f32_e32 v36, v36, v2
	v_fmac_f32_e32 v2, v34, v0
	v_mov_b32_e32 v0, v153
	v_lshlrev_b32_e32 v34, 16, v64
	v_fmac_f32_e32 v2, v36, v35
	v_mul_f32_e32 v35, v0, v2
	v_mul_f32_e32 v0, v35, v35
	s_nop 1
	v_mov_b32_dpp v0, v0 row_ror:8 row_mask:0xf bank_mask:0xf bound_ctrl:1
	v_fmac_f32_e32 v0, v35, v35
	s_nop 1
	v_add_f32_dpp v0, v0, v0 row_ror:4 row_mask:0xf bank_mask:0xf bound_ctrl:1
	s_nop 1
	v_add_f32_dpp v0, v0, v0 row_ror:2 row_mask:0xf bank_mask:0xf bound_ctrl:1
	s_nop 1
	v_add_f32_dpp v0, v0, v0 row_ror:1 row_mask:0xf bank_mask:0xf bound_ctrl:1
	s_nop 0
	v_readlane_b32 s72, v0, 16
	v_readlane_b32 s87, v0, 48
	v_readlane_b32 s1, v0, 0
	v_readlane_b32 s86, v0, 32
	v_mov_b32_e32 v0, s72
	v_mov_b32_e32 v36, s87
	v_add_f32_e32 v0, s1, v0
	v_add_f32_e32 v36, s86, v36
	v_add_f32_e32 v0, v0, v36
	v_max_f32_e32 v0, 0x179abe15, v0
	v_rsq_f32_e32 v0, v0
	v_add_f32_e32 v36, -1.0, v34
	v_fma_f32 v36, v36, v37, 1.0
	v_mul_f32_e32 v2, v2, v36
	v_mul_f32_e32 v35, v35, v0
	v_mul_f32_e32 v34, v35, v34
	v_mul_f32_e32 v35, v1, v34
	s_nop 1
	v_mov_b32_dpp v35, v35 row_ror:8 row_mask:0xf bank_mask:0xf bound_ctrl:1
	v_fmac_f32_e32 v35, v1, v34
	v_mul_f32_e32 v1, v1, v2
	v_mov_b32_e32 v2, v154
	v_add_f32_dpp v34, v35, v35 row_ror:4 row_mask:0xf bank_mask:0xf bound_ctrl:1
	s_nop 1
	v_add_f32_dpp v34, v34, v34 row_ror:2 row_mask:0xf bank_mask:0xf bound_ctrl:1
	s_nop 1
	v_add_f32_dpp v34, v34, v34 row_ror:1 row_mask:0xf bank_mask:0xf bound_ctrl:1
	s_nop 0
	v_readlane_b32 s86, v34, 0
	v_readlane_b32 s72, v34, 16
	v_readlane_b32 s88, v34, 32
	v_readlane_b32 s1, v34, 48
	v_mul_f32_e32 v34, v1, v2
	s_nop 1
	v_mov_b32_dpp v34, v34 row_ror:8 row_mask:0xf bank_mask:0xf bound_ctrl:1
	v_fmac_f32_e32 v34, v1, v2
	s_nop 1
	v_add_f32_dpp v1, v34, v34 row_ror:4 row_mask:0xf bank_mask:0xf bound_ctrl:1
	s_nop 1
	v_add_f32_dpp v1, v1, v1 row_ror:2 row_mask:0xf bank_mask:0xf bound_ctrl:1
	s_nop 1
	v_add_f32_dpp v1, v1, v1 row_ror:1 row_mask:0xf bank_mask:0xf bound_ctrl:1
	s_nop 0
	v_readlane_b32 s87, v1, 0
	v_readlane_b32 s92, v1, 16
	v_readlane_b32 s89, v1, 32
	v_readlane_b32 s93, v1, 48
	s_and_saveexec_b64 s[90:91], s[8:9]
	s_cbranch_execz .LBB0_1862
	v_mov_b32_e32 v34, s72
	v_mov_b32_e32 v35, s92
	v_mov_b32_e32 v36, s1
	v_mov_b32_e32 v37, s93
	v_pk_add_f32 v[34:35], s[86:87], v[34:35]
	v_pk_add_f32 v[36:37], s[88:89], v[36:37]
	s_nop 0
	v_pk_add_f32 v[34:35], v[34:35], v[36:37]
	s_nop 0
	v_mov_b32_e32 v1, v34
	v_add_co_u32_e32 v34, vcc, 0x1c500000, v32
	v_mov_b32_e32 v2, v35
	s_nop 0
	v_addc_co_u32_e32 v35, vcc, 0, v33, vcc
	global_store_dwordx4 v[34:35], v[0:3], off offset:80
.LBB0_1862:
	s_or_b64 exec, exec, s[90:91]
	s_nop 0
	v_mov_b32_e32 v0, v155
	v_lshlrev_b32_e32 v2, 16, v62
	v_mov_b32_e32 v34, v156
	v_lshlrev_b32_e32 v1, 16, v63
	v_cndmask_b32_e64 v2, 0, v2, s[12:13]
	v_lshlrev_b32_e32 v35, 16, v61
	v_sub_f32_e32 v2, v2, v1
	v_cndmask_b32_e64 v35, 0, v35, s[14:15]
	v_sub_f32_e32 v35, v35, v1
	v_lshlrev_b32_e32 v36, 16, v58
	v_cndmask_b32_e64 v36, 0, v36, s[14:15]
	v_mov_b32_e32 v37, v157
	s_waitcnt vmcnt(0)
	v_fmac_f32_e32 v1, v2, v0
	v_mov_b32_e32 v0, v158
	v_fmac_f32_e32 v1, v35, v34
	v_lshlrev_b32_e32 v34, 16, v59
	v_lshlrev_b32_e32 v2, 16, v60
	v_cndmask_b32_e64 v34, 0, v34, s[12:13]
	v_sub_f32_e32 v34, v34, v2
	v_mov_b32_e32 v35, v159
	v_sub_f32_e32 v36, v36, v2
	v_fmac_f32_e32 v2, v34, v0
	v_mov_b32_e32 v0, v160
	v_lshlrev_b32_e32 v34, 16, v57
	v_fmac_f32_e32 v2, v36, v35
	v_mul_f32_e32 v35, v0, v2
	v_mul_f32_e32 v0, v35, v35
	s_nop 1
	v_mov_b32_dpp v0, v0 row_ror:8 row_mask:0xf bank_mask:0xf bound_ctrl:1
	v_fmac_f32_e32 v0, v35, v35
	s_nop 1
	v_add_f32_dpp v0, v0, v0 row_ror:4 row_mask:0xf bank_mask:0xf bound_ctrl:1
	s_nop 1
	v_add_f32_dpp v0, v0, v0 row_ror:2 row_mask:0xf bank_mask:0xf bound_ctrl:1
	s_nop 1
	v_add_f32_dpp v0, v0, v0 row_ror:1 row_mask:0xf bank_mask:0xf bound_ctrl:1
	s_nop 0
	v_readlane_b32 s72, v0, 16
	v_readlane_b32 s87, v0, 48
	v_readlane_b32 s1, v0, 0
	v_readlane_b32 s86, v0, 32
	v_mov_b32_e32 v0, s72
	v_mov_b32_e32 v36, s87
	v_add_f32_e32 v0, s1, v0
	v_add_f32_e32 v36, s86, v36
	v_add_f32_e32 v0, v0, v36
	v_max_f32_e32 v0, 0x179abe15, v0
	v_rsq_f32_e32 v0, v0
	v_add_f32_e32 v36, -1.0, v34
	v_fma_f32 v36, v36, v37, 1.0
	v_mul_f32_e32 v2, v2, v36
	v_mul_f32_e32 v35, v35, v0
	v_mul_f32_e32 v34, v35, v34
	v_mul_f32_e32 v35, v1, v34
	s_nop 1
	v_mov_b32_dpp v35, v35 row_ror:8 row_mask:0xf bank_mask:0xf bound_ctrl:1
	v_fmac_f32_e32 v35, v1, v34
	v_mul_f32_e32 v1, v1, v2
	v_mov_b32_e32 v2, v161
	v_add_f32_dpp v34, v35, v35 row_ror:4 row_mask:0xf bank_mask:0xf bound_ctrl:1
	s_nop 1
	v_add_f32_dpp v34, v34, v34 row_ror:2 row_mask:0xf bank_mask:0xf bound_ctrl:1
	s_nop 1
	v_add_f32_dpp v34, v34, v34 row_ror:1 row_mask:0xf bank_mask:0xf bound_ctrl:1
	s_nop 0
	v_readlane_b32 s86, v34, 0
	v_readlane_b32 s72, v34, 16
	v_readlane_b32 s88, v34, 32
	v_readlane_b32 s1, v34, 48
	v_mul_f32_e32 v34, v1, v2
	s_nop 1
	v_mov_b32_dpp v34, v34 row_ror:8 row_mask:0xf bank_mask:0xf bound_ctrl:1
	v_fmac_f32_e32 v34, v1, v2
	s_nop 1
	v_add_f32_dpp v1, v34, v34 row_ror:4 row_mask:0xf bank_mask:0xf bound_ctrl:1
	s_nop 1
	v_add_f32_dpp v1, v1, v1 row_ror:2 row_mask:0xf bank_mask:0xf bound_ctrl:1
	s_nop 1
	v_add_f32_dpp v1, v1, v1 row_ror:1 row_mask:0xf bank_mask:0xf bound_ctrl:1
	s_nop 0
	v_readlane_b32 s87, v1, 0
	v_readlane_b32 s92, v1, 16
	v_readlane_b32 s89, v1, 32
	v_readlane_b32 s93, v1, 48
	s_and_saveexec_b64 s[90:91], s[8:9]
	s_cbranch_execz .LBB0_1864
	v_mov_b32_e32 v34, s72
	v_mov_b32_e32 v35, s92
	v_mov_b32_e32 v36, s1
	v_mov_b32_e32 v37, s93
	v_pk_add_f32 v[34:35], s[86:87], v[34:35]
	v_pk_add_f32 v[36:37], s[88:89], v[36:37]
	s_nop 0
	v_pk_add_f32 v[34:35], v[34:35], v[36:37]
	s_nop 0
	v_mov_b32_e32 v1, v34
	v_add_co_u32_e32 v34, vcc, 0x1c500000, v32
	v_mov_b32_e32 v2, v35
	s_nop 0
	v_addc_co_u32_e32 v35, vcc, 0, v33, vcc
	global_store_dwordx4 v[34:35], v[0:3], off offset:96
; DEV float bf2f(bf16_t b) { return __uint_as_float(((unsigned)b) << 16); }
; DEV void phase_rw_pre(const Params& p) {
;     ...
;     for (int h = 0; h < 8; ++h) {
;       const int hc = h * 64 + lane;
;       float x = bf2f(raw[h][0]);
;       const float r = x + p.in[14][hc] * ((hp ? bf2f(raw[h][1]) : 0.f) - x) + p.in[15][hc] * ((hn ? bf2f(raw[h][2]) : 0.f) - x);
;       x = bf2f(raw[h][3]);
;       const float kr = x + p.in[14][512 + hc] * ((hp ? bf2f(raw[h][4]) : 0.f) - x) + p.in[15][512 + hc] * ((hn ? bf2f(raw[h][5]) : 0.f) - x);
;       const float a = bf2f(raw[h][6]);
;       const float kkr = kr * p.in[23][hc];
;       const float inv = rsqrtf(fmaxf(wave_sum_dpp(kkr * kkr), 1e-24f));
;       const float kk = kkr * inv;
;       const float k2 = kr * (1.f + (a - 1.f) * p.in[24][hc]);
;       const float kar = wave_sum_dpp(kk * a * r);
;       const float bo = wave_sum_dpp(r * k2 * p.in[25][hc]);
;       if (lane == 0) *(float4*)(scal + ((size_t)t * 8 + h) * 4) = make_float4(inv, kar, bo, 0.f);
.LBB0_1864:
	s_or_b64 exec, exec, s[90:91]
	s_nop 0
	v_mov_b32_e32 v0, v162
	v_lshlrev_b32_e32 v2, 16, v55
	v_mov_b32_e32 v34, v163
	v_lshlrev_b32_e32 v1, 16, v56
	v_cndmask_b32_e64 v2, 0, v2, s[12:13]
	v_lshlrev_b32_e32 v35, 16, v54
	v_sub_f32_e32 v2, v2, v1
	v_cndmask_b32_e64 v35, 0, v35, s[14:15]
	v_sub_f32_e32 v35, v35, v1
	v_lshlrev_b32_e32 v36, 16, v51
	v_cndmask_b32_e64 v36, 0, v36, s[14:15]
	v_mov_b32_e32 v37, v164
	s_waitcnt vmcnt(0)
	v_fmac_f32_e32 v1, v2, v0
	global_load_dword v0, v[16:17], off
	v_fmac_f32_e32 v1, v35, v34
	v_lshlrev_b32_e32 v34, 16, v52
	v_lshlrev_b32_e32 v2, 16, v53
	v_cndmask_b32_e64 v34, 0, v34, s[12:13]
	v_sub_f32_e32 v34, v34, v2
	global_load_dword v35, v[18:19], off
	v_sub_f32_e32 v36, v36, v2
	s_waitcnt vmcnt(1)
	v_fmac_f32_e32 v2, v34, v0
	v_mov_b32_e32 v0, v165
	v_lshlrev_b32_e32 v34, 16, v50
	s_waitcnt vmcnt(0)
	v_fmac_f32_e32 v2, v36, v35
	v_mul_f32_e32 v35, v0, v2
	v_mul_f32_e32 v0, v35, v35
	s_nop 1
	v_mov_b32_dpp v0, v0 row_ror:8 row_mask:0xf bank_mask:0xf bound_ctrl:1
	v_fmac_f32_e32 v0, v35, v35
	s_nop 1
	v_add_f32_dpp v0, v0, v0 row_ror:4 row_mask:0xf bank_mask:0xf bound_ctrl:1
	s_nop 1
	v_add_f32_dpp v0, v0, v0 row_ror:2 row_mask:0xf bank_mask:0xf bound_ctrl:1
	s_nop 1
	v_add_f32_dpp v0, v0, v0 row_ror:1 row_mask:0xf bank_mask:0xf bound_ctrl:1
	s_nop 0
	v_readlane_b32 s12, v0, 16
	v_readlane_b32 s14, v0, 48
	v_readlane_b32 s1, v0, 0
	v_readlane_b32 s13, v0, 32
	v_mov_b32_e32 v0, s12
	v_mov_b32_e32 v36, s14
	v_add_f32_e32 v0, s1, v0
	v_add_f32_e32 v36, s13, v36
	v_add_f32_e32 v0, v0, v36
	v_max_f32_e32 v0, 0x179abe15, v0
	v_rsq_f32_e32 v0, v0
	v_add_f32_e32 v36, -1.0, v34
	v_fma_f32 v36, v36, v37, 1.0
	v_mul_f32_e32 v2, v2, v36
	v_mul_f32_e32 v35, v35, v0
	v_mul_f32_e32 v34, v35, v34
	v_mul_f32_e32 v35, v1, v34
	s_nop 1
	v_mov_b32_dpp v35, v35 row_ror:8 row_mask:0xf bank_mask:0xf bound_ctrl:1
	v_fmac_f32_e32 v35, v1, v34
	v_mul_f32_e32 v1, v1, v2
	v_mov_b32_e32 v2, v166
	v_add_f32_dpp v34, v35, v35 row_ror:4 row_mask:0xf bank_mask:0xf bound_ctrl:1
	s_nop 1
	v_add_f32_dpp v34, v34, v34 row_ror:2 row_mask:0xf bank_mask:0xf bound_ctrl:1
	s_nop 1
	v_add_f32_dpp v34, v34, v34 row_ror:1 row_mask:0xf bank_mask:0xf bound_ctrl:1
	s_nop 0
	v_readlane_b32 s12, v34, 0
	v_readlane_b32 s72, v34, 16
	v_readlane_b32 s14, v34, 32
	v_readlane_b32 s1, v34, 48
	v_mul_f32_e32 v34, v1, v2
	s_nop 1
	v_mov_b32_dpp v34, v34 row_ror:8 row_mask:0xf bank_mask:0xf bound_ctrl:1
	v_fmac_f32_e32 v34, v1, v2
	s_nop 1
	v_add_f32_dpp v1, v34, v34 row_ror:4 row_mask:0xf bank_mask:0xf bound_ctrl:1
	s_nop 1
	v_add_f32_dpp v1, v1, v1 row_ror:2 row_mask:0xf bank_mask:0xf bound_ctrl:1
	s_nop 1
	v_add_f32_dpp v1, v1, v1 row_ror:1 row_mask:0xf bank_mask:0xf bound_ctrl:1
	s_nop 0
	v_readlane_b32 s13, v1, 0
	v_readlane_b32 s88, v1, 16
	v_readlane_b32 s15, v1, 32
	v_readlane_b32 s89, v1, 48
	s_and_saveexec_b64 s[86:87], s[8:9]
	s_cbranch_execz .LBB0_1849
	v_mov_b32_e32 v34, s72
	v_mov_b32_e32 v35, s88
	v_mov_b32_e32 v36, s1
	v_mov_b32_e32 v37, s89
	v_pk_add_f32 v[34:35], s[12:13], v[34:35]
	v_pk_add_f32 v[36:37], s[14:15], v[36:37]
	v_add_co_u32_e32 v32, vcc, 0x1c500000, v32
	v_pk_add_f32 v[34:35], v[34:35], v[36:37]
	s_nop 0
	v_addc_co_u32_e32 v33, vcc, 0, v33, vcc
	v_mov_b32_e32 v1, v34
	v_mov_b32_e32 v2, v35
	global_store_dwordx4 v[32:33], v[0:3], off offset:112
	s_branch .LBB0_1849

.LBB0_1983:
	v_add_u32_e32 v9, s29, v5
	v_add_u32_e32 v77, s28, v66
	v_add_u32_e32 v6, 16, v9
	v_add_u32_e32 v18, 0x1fef, v77
	v_cndmask_b32_e32 v6, v18, v6, vcc
	v_add_u32_e32 v18, s3, v6
	v_cmp_lt_i32_e64 s[18:19], 0, v6
	v_ashrrev_i32_e32 v19, 31, v18
	v_mad_i64_i32 v[28:29], s[10:11], v18, s88, v[16:17]
	v_cndmask_b32_e64 v21, 0, -1, s[18:19]
	v_cndmask_b32_e64 v20, 0, v73, s[18:19]
	v_cmp_gt_i32_e64 s[20:21], s94, v6
	v_lshl_add_u64 v[154:155], v[28:29], 0, v[20:21]
	v_lshlrev_b64 v[20:21], 10, v[18:19]
	v_lshlrev_b64 v[18:19], 7, v[18:19]
	v_cndmask_b32_e64 v6, 0, v74, s[20:21]
	v_lshl_add_u64 v[18:19], s[92:93], 0, v[18:19]
	v_lshl_add_u64 v[156:157], v[28:29], 0, v[6:7]
	global_load_dwordx2 v[22:23], v[18:19], off
	v_add_u32_e32 v6, 17, v9
	v_add_u32_e32 v18, 0x1fee, v77
	v_cndmask_b32_e32 v6, v18, v6, vcc
	v_or_b32_e32 v20, v20, v14
	v_add_u32_e32 v18, s3, v6
	v_lshl_add_u64 v[158:159], s[90:91], 0, v[20:21]
	v_lshl_add_u64 v[160:161], s[24:25], 0, v[20:21]
	v_mad_i64_i32 v[20:21], s[10:11], v18, s88, v[16:17]
	v_ashrrev_i32_e32 v19, 31, v18
	global_load_ushort v101, v[20:21], off
	global_load_ushort v98, v[20:21], off offset:1024
	global_load_ushort v86, v[20:21], off offset:2048
	v_lshlrev_b64 v[20:21], 10, v[18:19]
	v_or_b32_e32 v20, v20, v14
	v_lshlrev_b64 v[18:19], 7, v[18:19]
	v_lshl_add_u64 v[24:25], s[90:91], 0, v[20:21]
	v_lshl_add_u64 v[20:21], s[24:25], 0, v[20:21]
	v_lshl_add_u64 v[18:19], s[92:93], 0, v[18:19]
	global_load_ushort v85, v[24:25], off
	global_load_ushort v97, v[20:21], off
	v_add_u32_e32 v6, 18, v9
	global_load_dwordx2 v[24:25], v[18:19], off
	v_add_u32_e32 v18, 0x1fed, v77
	v_cndmask_b32_e32 v6, v18, v6, vcc
	v_add_u32_e32 v18, s3, v6
	v_mad_i64_i32 v[20:21], s[12:13], v18, s88, v[16:17]
	v_ashrrev_i32_e32 v19, 31, v18
	global_load_ushort v102, v[20:21], off
	global_load_ushort v103, v[20:21], off offset:1024
	global_load_ushort v93, v[20:21], off offset:2048
	v_lshlrev_b64 v[20:21], 10, v[18:19]
	v_or_b32_e32 v20, v20, v14
	v_lshlrev_b64 v[18:19], 7, v[18:19]
	v_add_u32_e32 v6, 19, v9
	v_add_u32_e32 v9, 0x1fec, v77
	v_lshl_add_u64 v[26:27], s[90:91], 0, v[20:21]
	v_lshl_add_u64 v[20:21], s[24:25], 0, v[20:21]
	v_lshl_add_u64 v[18:19], s[92:93], 0, v[18:19]
	v_cndmask_b32_e32 v6, v9, v6, vcc
	global_load_ushort v81, v[26:27], off
	global_load_ushort v95, v[20:21], off
	s_mov_b32 s31, s30
	global_load_dwordx2 v[20:21], v[18:19], off
	v_add_u32_e32 v18, s3, v6
	v_mad_i64_i32 v[26:27], s[22:23], v18, s88, v[16:17]
	v_cmp_lt_i32_e64 s[22:23], 0, v6
	v_ashrrev_i32_e32 v19, 31, v18
	global_load_ushort v82, v[26:27], off
	v_cndmask_b32_e64 v79, 0, -1, s[22:23]
	v_cndmask_b32_e64 v78, 0, v73, s[22:23]
	v_cmp_gt_i32_e64 s[22:23], s94, v6
	v_lshl_add_u64 v[110:111], v[26:27], 0, v[78:79]
	global_load_ushort v92, v[110:111], off
	v_cndmask_b32_e64 v6, 0, v74, s[22:23]
	v_lshl_add_u64 v[112:113], v[26:27], 0, v[6:7]
	global_load_ushort v88, v[112:113], off
	global_load_ushort v89, v[26:27], off offset:1024
	global_load_ushort v90, v[110:111], off offset:1024
	global_load_ushort v84, v[112:113], off offset:1024
	global_load_ushort v78, v[26:27], off offset:2048
	global_load_ushort v79, v[110:111], off offset:2048
	global_load_ushort v77, v[112:113], off offset:2048
	v_lshlrev_b64 v[26:27], 10, v[18:19]
	v_or_b32_e32 v26, v26, v14
	v_lshlrev_b64 v[18:19], 7, v[18:19]
	s_and_b32 s22, s31, 1
	v_lshl_add_u64 v[110:111], s[90:91], 0, v[26:27]
	v_lshl_add_u64 v[26:27], s[24:25], 0, v[26:27]
	v_lshl_add_u64 v[18:19], s[92:93], 0, v[18:19]
	s_mul_i32 s23, s22, 0x6100
	global_load_ushort v9, v[110:111], off
	global_load_ushort v80, v[26:27], off
	v_mov_b32_e32 v6, s23
	global_load_dwordx2 v[18:19], v[18:19], off
	v_lshl_or_b32 v26, v52, 2, s23
	v_lshl_add_u32 v27, v15, 2, s23
	ds_read_b128 v[110:113], v26
	ds_read_b128 v[114:117], v26 offset:256
	ds_read_b128 v[122:125], v26 offset:512
	ds_read_b128 v[118:121], v26 offset:768
	ds_read_b128 v[126:129], v26 offset:1024
	ds_read_b32 v134, v27 offset:1280
	ds_read_b32 v141, v6 offset:1536
	s_waitcnt lgkmcnt(5)
	v_pk_mul_f32 v[114:115], v[0:1], v[114:115]
	ds_read_b128 v[130:133], v26 offset:1552
	ds_read_b128 v[136:139], v26 offset:1808
	ds_read_b128 v[142:145], v26 offset:2064
	ds_read_b128 v[146:149], v26 offset:2320
	ds_read_b128 v[150:153], v26 offset:2576
	ds_read_b32 v162, v27 offset:2832
	ds_read_b32 v166, v6 offset:3088
	v_pk_fma_f32 v[114:115], v[2:3], v[116:117], v[114:115]
	s_waitcnt lgkmcnt(8)
	v_pk_mul_f32 v[118:119], v[118:119], v[134:135] op_sel_hi:[1,0]
	v_pk_mul_f32 v[120:121], v[120:121], v[134:135] op_sel_hi:[1,0]
	v_pk_fma_f32 v[0:1], v[0:1], v[110:111], v[118:119]
	v_pk_fma_f32 v[2:3], v[2:3], v[112:113], v[120:121]
	v_pk_mul_f32 v[110:111], v[126:127], v[0:1]
	v_add_f32_e32 v134, v114, v115
	v_pk_fma_f32 v[110:111], v[128:129], v[2:3], v[110:111]
	s_mulk_i32 s22, 0xa300
	v_add_f32_e32 v121, v110, v111
	global_load_ushort v119, v[28:29], off
	global_load_ushort v120, v[154:155], off
	global_load_ushort v118, v[156:157], off
	global_load_ushort v116, v[28:29], off offset:1024
	global_load_ushort v117, v[154:155], off offset:1024
	global_load_ushort v115, v[156:157], off offset:1024
	global_load_ushort v112, v[28:29], off offset:2048
	global_load_ushort v113, v[154:155], off offset:2048
	global_load_ushort v114, v[156:157], off offset:2048
	global_load_ushort v111, v[160:161], off
	global_load_ushort v110, v[158:159], off
	s_nop 0
	v_add_f32_dpp v134, v134, v134 row_ror:8 row_mask:0xf bank_mask:0xf
	v_add_f32_dpp v121, v121, v121 row_ror:8 row_mask:0xf bank_mask:0xf
	s_nop 0
	v_add_f32_dpp v134, v134, v134 row_ror:4 row_mask:0xf bank_mask:0xf
	v_add_f32_dpp v121, v121, v121 row_ror:4 row_mask:0xf bank_mask:0xf
	s_nop 0
	v_add_f32_dpp v134, v134, v134 row_ror:2 row_mask:0xf bank_mask:0xf
	v_add_f32_dpp v121, v121, v121 row_ror:2 row_mask:0xf bank_mask:0xf
	s_nop 0
	v_add_f32_dpp v134, v134, v134 row_ror:1 row_mask:0xf bank_mask:0xf
	v_add_f32_dpp v121, v121, v121 row_ror:1 row_mask:0xf bank_mask:0xf
	s_add_i32 s22, s23, s22
	v_pk_fma_f32 v[28:29], v[122:123], v[134:135], v[0:1] op_sel_hi:[1,0,1]
	v_pk_fma_f32 v[164:165], v[124:125], v[134:135], v[2:3] op_sel_hi:[1,0,1]
	s_waitcnt lgkmcnt(5)
; template <int RPL>
; DEV void step_load(StepV<RPL>& x, const float* sb, int jl, int rowbase) {
;   x.w = *(const f32x4v*)(sb + jl * 4);
;   x.nk = *(const f32x4v*)(sb + 64 + jl * 4);
;   x.ka = *(const f32x4v*)(sb + 128 + jl * 4);
;   x.k = *(const f32x4v*)(sb + 192 + jl * 4);
;   x.r = *(const f32x4v*)(sb + 256 + jl * 4);
; #pragma unroll
;   for (int r = 0; r < RPL; ++r) x.v[r] = sb[320 + rowbase + r];
;   x.kar = sb[384];
; }
	v_pk_mul_f32 v[136:137], v[136:137], v[28:29]
	v_pk_mul_f32 v[28:29], v[130:131], v[28:29]
	v_lshl_add_u32 v109, v58, 2, s22
	v_fmac_f32_e32 v121, v141, v134
	v_pk_mul_f32 v[130:131], v[132:133], v[164:165]
	s_waitcnt lgkmcnt(1)
	v_pk_fma_f32 v[28:29], v[146:147], v[162:163], v[28:29] op_sel_hi:[1,0,1]
	ds_write_b32 v109, v121 offset:49664
	v_pk_fma_f32 v[130:131], v[148:149], v[162:163], v[130:131] op_sel_hi:[1,0,1]
	v_pk_mul_f32 v[132:133], v[150:151], v[28:29]
	ds_read_b128 v[0:3], v26 offset:3104
	ds_read_b128 v[122:125], v26 offset:3360
	ds_read_b128 v[126:129], v26 offset:3616
	ds_read_b128 v[154:157], v26 offset:3872
	ds_read_b128 v[158:161], v26 offset:4128
	ds_read_b32 v134, v27 offset:4384
	ds_read_b32 v121, v6 offset:4640
	v_pk_fma_f32 v[136:137], v[138:139], v[164:165], v[136:137]
	v_pk_fma_f32 v[132:133], v[152:153], v[130:131], v[132:133]
	v_add_f32_e32 v136, v136, v137
	v_add_f32_e32 v132, v132, v133
	s_nop 0
	v_add_f32_dpp v136, v136, v136 row_ror:8 row_mask:0xf bank_mask:0xf
	v_add_f32_dpp v132, v132, v132 row_ror:8 row_mask:0xf bank_mask:0xf
	s_nop 0
	v_add_f32_dpp v136, v136, v136 row_ror:4 row_mask:0xf bank_mask:0xf
	v_add_f32_dpp v132, v132, v132 row_ror:4 row_mask:0xf bank_mask:0xf
	s_nop 0
	v_add_f32_dpp v136, v136, v136 row_ror:2 row_mask:0xf bank_mask:0xf
	v_add_f32_dpp v132, v132, v132 row_ror:2 row_mask:0xf bank_mask:0xf
	s_nop 0
	v_add_f32_dpp v136, v136, v136 row_ror:1 row_mask:0xf bank_mask:0xf
	v_add_f32_dpp v132, v132, v132 row_ror:1 row_mask:0xf bank_mask:0xf
	s_add_i32 s30, s30, 1
	v_pk_fma_f32 v[28:29], v[142:143], v[136:137], v[28:29] op_sel_hi:[1,0,1]
	v_pk_fma_f32 v[162:163], v[144:145], v[136:137], v[130:131] op_sel_hi:[1,0,1]
	s_waitcnt lgkmcnt(6)
	v_pk_mul_f32 v[0:1], v[0:1], v[28:29]
	v_fmac_f32_e32 v132, v166, v136
	v_pk_mul_f32 v[2:3], v[2:3], v[162:163]
	s_waitcnt lgkmcnt(1)
	v_pk_fma_f32 v[0:1], v[154:155], v[134:135], v[0:1] op_sel_hi:[1,0,1]
	ds_write_b32 v109, v132 offset:49728
	v_pk_mul_f32 v[122:123], v[122:123], v[28:29]
	v_pk_fma_f32 v[2:3], v[156:157], v[134:135], v[2:3] op_sel_hi:[1,0,1]
	v_pk_mul_f32 v[28:29], v[158:159], v[0:1]
	ds_read_b128 v[130:133], v26 offset:4656
	ds_read_b128 v[136:139], v26 offset:4912
	ds_read_b128 v[142:145], v26 offset:5168
	ds_read_b128 v[146:149], v26 offset:5424
	ds_read_b128 v[150:153], v26 offset:5680
	ds_read_b32 v164, v27 offset:5936
	ds_read_b32 v141, v6 offset:6192
	v_pk_fma_f32 v[122:123], v[124:125], v[162:163], v[122:123]
	v_pk_fma_f32 v[28:29], v[160:161], v[2:3], v[28:29]
	v_add_f32_e32 v122, v122, v123
	v_add_f32_e32 v123, v28, v29
	s_nop 0
	v_add_f32_dpp v122, v122, v122 row_ror:8 row_mask:0xf bank_mask:0xf
	v_add_f32_dpp v123, v123, v123 row_ror:8 row_mask:0xf bank_mask:0xf
	s_nop 0
	v_add_f32_dpp v122, v122, v122 row_ror:4 row_mask:0xf bank_mask:0xf
	v_add_f32_dpp v123, v123, v123 row_ror:4 row_mask:0xf bank_mask:0xf
	s_nop 0
	v_add_f32_dpp v122, v122, v122 row_ror:2 row_mask:0xf bank_mask:0xf
	v_add_f32_dpp v123, v123, v123 row_ror:2 row_mask:0xf bank_mask:0xf
	s_nop 0
	v_add_f32_dpp v122, v122, v122 row_ror:1 row_mask:0xf bank_mask:0xf
	v_add_f32_dpp v123, v123, v123 row_ror:1 row_mask:0xf bank_mask:0xf
	s_bitcmp1_b32 s30, 0
	v_pk_fma_f32 v[28:29], v[126:127], v[122:123], v[0:1] op_sel_hi:[1,0,1]
	v_pk_fma_f32 v[162:163], v[128:129], v[122:123], v[2:3] op_sel_hi:[1,0,1]
	s_waitcnt lgkmcnt(5)
	v_pk_mul_f32 v[136:137], v[136:137], v[28:29]
	v_pk_mul_f32 v[28:29], v[130:131], v[28:29]
	v_fmac_f32_e32 v123, v121, v122
	v_pk_mul_f32 v[130:131], v[132:133], v[162:163]
	s_waitcnt lgkmcnt(1)
	v_pk_fma_f32 v[28:29], v[146:147], v[164:165], v[28:29] op_sel_hi:[1,0,1]
	ds_write_b32 v109, v123 offset:49792
	v_pk_fma_f32 v[130:131], v[148:149], v[164:165], v[130:131] op_sel_hi:[1,0,1]
	v_pk_mul_f32 v[132:133], v[150:151], v[28:29]
	ds_read_b128 v[0:3], v26 offset:6208
	ds_read_b128 v[122:125], v26 offset:6464
	ds_read_b128 v[126:129], v26 offset:6720
	ds_read_b128 v[154:157], v26 offset:6976
	ds_read_b128 v[158:161], v26 offset:7232
	ds_read_b32 v134, v27 offset:7488
	ds_read_b32 v121, v6 offset:7744
	v_pk_fma_f32 v[136:137], v[138:139], v[162:163], v[136:137]
	v_pk_fma_f32 v[132:133], v[152:153], v[130:131], v[132:133]
	v_add_f32_e32 v136, v136, v137
	v_add_f32_e32 v132, v132, v133
	s_nop 0
	v_add_f32_dpp v136, v136, v136 row_ror:8 row_mask:0xf bank_mask:0xf
	v_add_f32_dpp v132, v132, v132 row_ror:8 row_mask:0xf bank_mask:0xf
	s_nop 0
	v_add_f32_dpp v136, v136, v136 row_ror:4 row_mask:0xf bank_mask:0xf
	v_add_f32_dpp v132, v132, v132 row_ror:4 row_mask:0xf bank_mask:0xf
	s_nop 0
	v_add_f32_dpp v136, v136, v136 row_ror:2 row_mask:0xf bank_mask:0xf
	v_add_f32_dpp v132, v132, v132 row_ror:2 row_mask:0xf bank_mask:0xf
	s_nop 0
	v_add_f32_dpp v136, v136, v136 row_ror:1 row_mask:0xf bank_mask:0xf
	v_add_f32_dpp v132, v132, v132 row_ror:1 row_mask:0xf bank_mask:0xf
	s_cselect_b32 s23, 0x6100, 0
	v_pk_fma_f32 v[28:29], v[142:143], v[136:137], v[28:29] op_sel_hi:[1,0,1]
	v_pk_fma_f32 v[162:163], v[144:145], v[136:137], v[130:131] op_sel_hi:[1,0,1]
	s_waitcnt lgkmcnt(6)
	v_pk_mul_f32 v[0:1], v[0:1], v[28:29]
	v_fmac_f32_e32 v132, v141, v136
	v_pk_mul_f32 v[2:3], v[2:3], v[162:163]
	s_waitcnt lgkmcnt(1)
	v_pk_fma_f32 v[0:1], v[154:155], v[134:135], v[0:1] op_sel_hi:[1,0,1]
	ds_write_b32 v109, v132 offset:49856
	v_pk_mul_f32 v[122:123], v[122:123], v[28:29]
	v_pk_fma_f32 v[2:3], v[156:157], v[134:135], v[2:3] op_sel_hi:[1,0,1]
	v_pk_mul_f32 v[28:29], v[158:159], v[0:1]
	ds_read_b128 v[130:133], v26 offset:7760
	ds_read_b128 v[136:139], v26 offset:8016
	ds_read_b128 v[142:145], v26 offset:8272
	ds_read_b128 v[146:149], v26 offset:8528
	ds_read_b128 v[150:153], v26 offset:8784
	ds_read_b32 v164, v27 offset:9040
	ds_read_b32 v141, v6 offset:9296
	v_pk_fma_f32 v[122:123], v[124:125], v[162:163], v[122:123]
	v_pk_fma_f32 v[28:29], v[160:161], v[2:3], v[28:29]
	v_add_f32_e32 v122, v122, v123
	v_add_f32_e32 v123, v28, v29
	s_nop 0
	v_add_f32_dpp v122, v122, v122 row_ror:8 row_mask:0xf bank_mask:0xf
	v_add_f32_dpp v123, v123, v123 row_ror:8 row_mask:0xf bank_mask:0xf
	s_nop 0
	v_add_f32_dpp v122, v122, v122 row_ror:4 row_mask:0xf bank_mask:0xf
	v_add_f32_dpp v123, v123, v123 row_ror:4 row_mask:0xf bank_mask:0xf
	s_nop 0
	v_add_f32_dpp v122, v122, v122 row_ror:2 row_mask:0xf bank_mask:0xf
	v_add_f32_dpp v123, v123, v123 row_ror:2 row_mask:0xf bank_mask:0xf
	s_nop 0
	v_add_f32_dpp v122, v122, v122 row_ror:1 row_mask:0xf bank_mask:0xf
	v_add_f32_dpp v123, v123, v123 row_ror:1 row_mask:0xf bank_mask:0xf
	s_waitcnt vmcnt(10)
	v_mov_b32_e32 v251, v119
	v_lshlrev_b32_e32 v119, 16, v119
	v_pk_fma_f32 v[28:29], v[126:127], v[122:123], v[0:1] op_sel_hi:[1,0,1]
	v_pk_fma_f32 v[162:163], v[128:129], v[122:123], v[2:3] op_sel_hi:[1,0,1]
	s_waitcnt lgkmcnt(5)
	v_pk_mul_f32 v[136:137], v[136:137], v[28:29]
	v_pk_mul_f32 v[28:29], v[130:131], v[28:29]
	v_fmac_f32_e32 v123, v121, v122
	v_pk_mul_f32 v[130:131], v[132:133], v[162:163]
	s_waitcnt lgkmcnt(1)
	v_pk_fma_f32 v[28:29], v[146:147], v[164:165], v[28:29] op_sel_hi:[1,0,1]
	ds_write_b32 v109, v123 offset:49920
	v_pk_fma_f32 v[130:131], v[148:149], v[164:165], v[130:131] op_sel_hi:[1,0,1]
	v_pk_mul_f32 v[132:133], v[150:151], v[28:29]
	ds_read_b128 v[0:3], v26 offset:9312
	ds_read_b128 v[122:125], v26 offset:9568
	ds_read_b128 v[126:129], v26 offset:9824
	ds_read_b128 v[154:157], v26 offset:10080
	ds_read_b128 v[158:161], v26 offset:10336
	ds_read_b32 v134, v27 offset:10592
	ds_read_b32 v121, v6 offset:10848
	v_pk_fma_f32 v[136:137], v[138:139], v[162:163], v[136:137]
	v_pk_fma_f32 v[132:133], v[152:153], v[130:131], v[132:133]
	v_add_f32_e32 v136, v136, v137
	v_add_f32_e32 v132, v132, v133
	s_nop 0
	v_add_f32_dpp v136, v136, v136 row_ror:8 row_mask:0xf bank_mask:0xf
	v_add_f32_dpp v132, v132, v132 row_ror:8 row_mask:0xf bank_mask:0xf
	s_nop 0
	v_add_f32_dpp v136, v136, v136 row_ror:4 row_mask:0xf bank_mask:0xf
	v_add_f32_dpp v132, v132, v132 row_ror:4 row_mask:0xf bank_mask:0xf
	s_nop 0
	v_add_f32_dpp v136, v136, v136 row_ror:2 row_mask:0xf bank_mask:0xf
	v_add_f32_dpp v132, v132, v132 row_ror:2 row_mask:0xf bank_mask:0xf
	s_nop 0
	v_add_f32_dpp v136, v136, v136 row_ror:1 row_mask:0xf bank_mask:0xf
	v_add_f32_dpp v132, v132, v132 row_ror:1 row_mask:0xf bank_mask:0xf
	s_waitcnt vmcnt(8)
	v_lshlrev_b32_e32 v118, 16, v118
	v_pk_fma_f32 v[28:29], v[142:143], v[136:137], v[28:29] op_sel_hi:[1,0,1]
	v_pk_fma_f32 v[162:163], v[144:145], v[136:137], v[130:131] op_sel_hi:[1,0,1]
	s_waitcnt lgkmcnt(6)
	v_pk_mul_f32 v[0:1], v[0:1], v[28:29]
	v_fmac_f32_e32 v132, v141, v136
	v_pk_mul_f32 v[2:3], v[2:3], v[162:163]
	s_waitcnt lgkmcnt(1)
	v_pk_fma_f32 v[0:1], v[154:155], v[134:135], v[0:1] op_sel_hi:[1,0,1]
	ds_write_b32 v109, v132 offset:49984
	v_pk_mul_f32 v[122:123], v[122:123], v[28:29]
	v_pk_fma_f32 v[2:3], v[156:157], v[134:135], v[2:3] op_sel_hi:[1,0,1]
	v_pk_mul_f32 v[28:29], v[158:159], v[0:1]
	ds_read_b128 v[130:133], v26 offset:10864
	ds_read_b128 v[136:139], v26 offset:11120
	ds_read_b128 v[142:145], v26 offset:11376
	ds_read_b128 v[146:149], v26 offset:11632
	ds_read_b128 v[150:153], v26 offset:11888
	ds_read_b32 v164, v27 offset:12144
	ds_read_b32 v141, v6 offset:12400
	v_pk_fma_f32 v[122:123], v[124:125], v[162:163], v[122:123]
	v_pk_fma_f32 v[28:29], v[160:161], v[2:3], v[28:29]
	v_add_f32_e32 v122, v122, v123
	v_add_f32_e32 v123, v28, v29
	s_nop 0
	v_add_f32_dpp v122, v122, v122 row_ror:8 row_mask:0xf bank_mask:0xf
	v_add_f32_dpp v123, v123, v123 row_ror:8 row_mask:0xf bank_mask:0xf
	s_nop 0
	v_add_f32_dpp v122, v122, v122 row_ror:4 row_mask:0xf bank_mask:0xf
	v_add_f32_dpp v123, v123, v123 row_ror:4 row_mask:0xf bank_mask:0xf
	s_nop 0
	v_add_f32_dpp v122, v122, v122 row_ror:2 row_mask:0xf bank_mask:0xf
	v_add_f32_dpp v123, v123, v123 row_ror:2 row_mask:0xf bank_mask:0xf
	s_nop 0
	v_add_f32_dpp v122, v122, v122 row_ror:1 row_mask:0xf bank_mask:0xf
	v_add_f32_dpp v123, v123, v123 row_ror:1 row_mask:0xf bank_mask:0xf
	v_pk_fma_f32 v[28:29], v[126:127], v[122:123], v[0:1] op_sel_hi:[1,0,1]
	v_pk_fma_f32 v[162:163], v[128:129], v[122:123], v[2:3] op_sel_hi:[1,0,1]
	s_waitcnt lgkmcnt(5)
	v_pk_mul_f32 v[136:137], v[136:137], v[28:29]
	v_pk_mul_f32 v[28:29], v[130:131], v[28:29]
	v_fmac_f32_e32 v123, v121, v122
	v_pk_mul_f32 v[130:131], v[132:133], v[162:163]
	s_waitcnt lgkmcnt(1)
	v_pk_fma_f32 v[28:29], v[146:147], v[164:165], v[28:29] op_sel_hi:[1,0,1]
	ds_write_b32 v109, v123 offset:50048
	v_pk_fma_f32 v[130:131], v[148:149], v[164:165], v[130:131] op_sel_hi:[1,0,1]
	v_pk_mul_f32 v[132:133], v[150:151], v[28:29]
	ds_read_b128 v[0:3], v26 offset:12416
	ds_read_b128 v[122:125], v26 offset:12672
	ds_read_b128 v[126:129], v26 offset:12928
	ds_read_b128 v[154:157], v26 offset:13184
	ds_read_b128 v[158:161], v26 offset:13440
	ds_read_b32 v134, v27 offset:13696
	ds_read_b32 v121, v6 offset:13952
	v_pk_fma_f32 v[136:137], v[138:139], v[162:163], v[136:137]
	v_pk_fma_f32 v[132:133], v[152:153], v[130:131], v[132:133]
	v_add_f32_e32 v136, v136, v137
	v_add_f32_e32 v132, v132, v133
	s_nop 0
	v_add_f32_dpp v136, v136, v136 row_ror:8 row_mask:0xf bank_mask:0xf
	v_add_f32_dpp v132, v132, v132 row_ror:8 row_mask:0xf bank_mask:0xf
	s_nop 0
	v_add_f32_dpp v136, v136, v136 row_ror:4 row_mask:0xf bank_mask:0xf
	v_add_f32_dpp v132, v132, v132 row_ror:4 row_mask:0xf bank_mask:0xf
	s_nop 0
	v_add_f32_dpp v136, v136, v136 row_ror:2 row_mask:0xf bank_mask:0xf
	v_add_f32_dpp v132, v132, v132 row_ror:2 row_mask:0xf bank_mask:0xf
	s_nop 0
	v_add_f32_dpp v136, v136, v136 row_ror:1 row_mask:0xf bank_mask:0xf
	v_add_f32_dpp v132, v132, v132 row_ror:1 row_mask:0xf bank_mask:0xf
	v_sub_f32_e32 v118, v118, v119
	v_pk_fma_f32 v[28:29], v[142:143], v[136:137], v[28:29] op_sel_hi:[1,0,1]
	v_pk_fma_f32 v[162:163], v[144:145], v[136:137], v[130:131] op_sel_hi:[1,0,1]
	s_waitcnt lgkmcnt(6)
	v_pk_mul_f32 v[0:1], v[0:1], v[28:29]
	v_fmac_f32_e32 v132, v141, v136
	v_pk_mul_f32 v[2:3], v[2:3], v[162:163]
	s_waitcnt lgkmcnt(1)
	v_pk_fma_f32 v[0:1], v[154:155], v[134:135], v[0:1] op_sel_hi:[1,0,1]
	ds_write_b32 v109, v132 offset:50112
	v_pk_mul_f32 v[122:123], v[122:123], v[28:29]
	v_pk_fma_f32 v[2:3], v[156:157], v[134:135], v[2:3] op_sel_hi:[1,0,1]
	v_pk_mul_f32 v[28:29], v[158:159], v[0:1]
	ds_read_b128 v[130:133], v26 offset:13968
	ds_read_b128 v[136:139], v26 offset:14224
	ds_read_b128 v[142:145], v26 offset:14480
	ds_read_b128 v[146:149], v26 offset:14736
	ds_read_b128 v[150:153], v26 offset:14992
	ds_read_b32 v164, v27 offset:15248
	ds_read_b32 v141, v6 offset:15504
	v_pk_fma_f32 v[122:123], v[124:125], v[162:163], v[122:123]
	v_pk_fma_f32 v[28:29], v[160:161], v[2:3], v[28:29]
	v_add_f32_e32 v122, v122, v123
	v_add_f32_e32 v123, v28, v29
	s_nop 0
	v_add_f32_dpp v122, v122, v122 row_ror:8 row_mask:0xf bank_mask:0xf
	v_add_f32_dpp v123, v123, v123 row_ror:8 row_mask:0xf bank_mask:0xf
	s_nop 0
	v_add_f32_dpp v122, v122, v122 row_ror:4 row_mask:0xf bank_mask:0xf
	v_add_f32_dpp v123, v123, v123 row_ror:4 row_mask:0xf bank_mask:0xf
	s_nop 0
	v_add_f32_dpp v122, v122, v122 row_ror:2 row_mask:0xf bank_mask:0xf
	v_add_f32_dpp v123, v123, v123 row_ror:2 row_mask:0xf bank_mask:0xf
	s_nop 0
	v_add_f32_dpp v122, v122, v122 row_ror:1 row_mask:0xf bank_mask:0xf
	v_add_f32_dpp v123, v123, v123 row_ror:1 row_mask:0xf bank_mask:0xf
	s_waitcnt vmcnt(7)
	v_mov_b32_e32 v252, v116
	v_lshlrev_b32_e32 v116, 16, v116
	v_pk_fma_f32 v[28:29], v[126:127], v[122:123], v[0:1] op_sel_hi:[1,0,1]
	v_pk_fma_f32 v[162:163], v[128:129], v[122:123], v[2:3] op_sel_hi:[1,0,1]
	s_waitcnt lgkmcnt(5)
	v_pk_mul_f32 v[136:137], v[136:137], v[28:29]
	v_pk_mul_f32 v[28:29], v[130:131], v[28:29]
	v_fmac_f32_e32 v123, v121, v122
	v_pk_mul_f32 v[130:131], v[132:133], v[162:163]
	s_waitcnt lgkmcnt(1)
	v_pk_fma_f32 v[28:29], v[146:147], v[164:165], v[28:29] op_sel_hi:[1,0,1]
	ds_write_b32 v109, v123 offset:50176
	v_pk_fma_f32 v[130:131], v[148:149], v[164:165], v[130:131] op_sel_hi:[1,0,1]
	v_pk_mul_f32 v[132:133], v[150:151], v[28:29]
	ds_read_b128 v[0:3], v26 offset:15520
	ds_read_b128 v[122:125], v26 offset:15776
	ds_read_b128 v[126:129], v26 offset:16032
	ds_read_b128 v[154:157], v26 offset:16288
	ds_read_b128 v[158:161], v26 offset:16544
	ds_read_b32 v134, v27 offset:16800
	ds_read_b32 v121, v6 offset:17056
	v_pk_fma_f32 v[136:137], v[138:139], v[162:163], v[136:137]
	v_pk_fma_f32 v[132:133], v[152:153], v[130:131], v[132:133]
	v_add_f32_e32 v136, v136, v137
	v_add_f32_e32 v132, v132, v133
	s_nop 0
	v_add_f32_dpp v136, v136, v136 row_ror:8 row_mask:0xf bank_mask:0xf
	v_add_f32_dpp v132, v132, v132 row_ror:8 row_mask:0xf bank_mask:0xf
	s_nop 0
	v_add_f32_dpp v136, v136, v136 row_ror:4 row_mask:0xf bank_mask:0xf
	v_add_f32_dpp v132, v132, v132 row_ror:4 row_mask:0xf bank_mask:0xf
	s_nop 0
	v_add_f32_dpp v136, v136, v136 row_ror:2 row_mask:0xf bank_mask:0xf
	v_add_f32_dpp v132, v132, v132 row_ror:2 row_mask:0xf bank_mask:0xf
	s_nop 0
	v_add_f32_dpp v136, v136, v136 row_ror:1 row_mask:0xf bank_mask:0xf
	v_add_f32_dpp v132, v132, v132 row_ror:1 row_mask:0xf bank_mask:0xf
	s_waitcnt vmcnt(5)
	v_lshlrev_b32_e32 v115, 16, v115
	v_pk_fma_f32 v[28:29], v[142:143], v[136:137], v[28:29] op_sel_hi:[1,0,1]
	v_pk_fma_f32 v[162:163], v[144:145], v[136:137], v[130:131] op_sel_hi:[1,0,1]
	s_waitcnt lgkmcnt(6)
	v_pk_mul_f32 v[0:1], v[0:1], v[28:29]
	v_fmac_f32_e32 v132, v141, v136
	v_pk_mul_f32 v[2:3], v[2:3], v[162:163]
	s_waitcnt lgkmcnt(1)
	v_pk_fma_f32 v[0:1], v[154:155], v[134:135], v[0:1] op_sel_hi:[1,0,1]
	ds_write_b32 v109, v132 offset:50240
	v_pk_mul_f32 v[122:123], v[122:123], v[28:29]
	v_pk_fma_f32 v[2:3], v[156:157], v[134:135], v[2:3] op_sel_hi:[1,0,1]
	v_pk_mul_f32 v[28:29], v[158:159], v[0:1]
	ds_read_b128 v[130:133], v26 offset:17072
	ds_read_b128 v[136:139], v26 offset:17328
	ds_read_b128 v[142:145], v26 offset:17584
	ds_read_b128 v[146:149], v26 offset:17840
	ds_read_b128 v[150:153], v26 offset:18096
	ds_read_b32 v164, v27 offset:18352
	ds_read_b32 v141, v6 offset:18608
	v_pk_fma_f32 v[122:123], v[124:125], v[162:163], v[122:123]
	v_pk_fma_f32 v[28:29], v[160:161], v[2:3], v[28:29]
	v_add_f32_e32 v122, v122, v123
	v_add_f32_e32 v123, v28, v29
	s_nop 0
	v_add_f32_dpp v122, v122, v122 row_ror:8 row_mask:0xf bank_mask:0xf
	v_add_f32_dpp v123, v123, v123 row_ror:8 row_mask:0xf bank_mask:0xf
	s_nop 0
	v_add_f32_dpp v122, v122, v122 row_ror:4 row_mask:0xf bank_mask:0xf
	v_add_f32_dpp v123, v123, v123 row_ror:4 row_mask:0xf bank_mask:0xf
	s_nop 0
	v_add_f32_dpp v122, v122, v122 row_ror:2 row_mask:0xf bank_mask:0xf
	v_add_f32_dpp v123, v123, v123 row_ror:2 row_mask:0xf bank_mask:0xf
	s_nop 0
	v_add_f32_dpp v122, v122, v122 row_ror:1 row_mask:0xf bank_mask:0xf
	v_add_f32_dpp v123, v123, v123 row_ror:1 row_mask:0xf bank_mask:0xf
	v_pk_fma_f32 v[28:29], v[126:127], v[122:123], v[0:1] op_sel_hi:[1,0,1]
	v_pk_fma_f32 v[162:163], v[128:129], v[122:123], v[2:3] op_sel_hi:[1,0,1]
	s_waitcnt lgkmcnt(5)
	v_pk_mul_f32 v[136:137], v[136:137], v[28:29]
	v_pk_mul_f32 v[28:29], v[130:131], v[28:29]
	v_fmac_f32_e32 v123, v121, v122
	v_pk_mul_f32 v[130:131], v[132:133], v[162:163]
	s_waitcnt lgkmcnt(1)
	v_pk_fma_f32 v[28:29], v[146:147], v[164:165], v[28:29] op_sel_hi:[1,0,1]
	ds_write_b32 v109, v123 offset:50304
	v_pk_fma_f32 v[130:131], v[148:149], v[164:165], v[130:131] op_sel_hi:[1,0,1]
	v_pk_mul_f32 v[132:133], v[150:151], v[28:29]
	ds_read_b128 v[0:3], v26 offset:18624
	ds_read_b128 v[122:125], v26 offset:18880
	ds_read_b128 v[126:129], v26 offset:19136
	ds_read_b128 v[154:157], v26 offset:19392
	ds_read_b128 v[158:161], v26 offset:19648
	ds_read_b32 v134, v27 offset:19904
	ds_read_b32 v121, v6 offset:20160
	v_pk_fma_f32 v[136:137], v[138:139], v[162:163], v[136:137]
	v_pk_fma_f32 v[132:133], v[152:153], v[130:131], v[132:133]
	v_add_f32_e32 v136, v136, v137
	v_add_f32_e32 v132, v132, v133
	s_nop 0
	v_add_f32_dpp v136, v136, v136 row_ror:8 row_mask:0xf bank_mask:0xf
	v_add_f32_dpp v132, v132, v132 row_ror:8 row_mask:0xf bank_mask:0xf
	s_nop 0
	v_add_f32_dpp v136, v136, v136 row_ror:4 row_mask:0xf bank_mask:0xf
	v_add_f32_dpp v132, v132, v132 row_ror:4 row_mask:0xf bank_mask:0xf
	s_nop 0
	v_add_f32_dpp v136, v136, v136 row_ror:2 row_mask:0xf bank_mask:0xf
	v_add_f32_dpp v132, v132, v132 row_ror:2 row_mask:0xf bank_mask:0xf
	s_nop 0
	v_add_f32_dpp v136, v136, v136 row_ror:1 row_mask:0xf bank_mask:0xf
	v_add_f32_dpp v132, v132, v132 row_ror:1 row_mask:0xf bank_mask:0xf
	v_sub_f32_e32 v115, v115, v116
	v_pk_fma_f32 v[28:29], v[142:143], v[136:137], v[28:29] op_sel_hi:[1,0,1]
	v_pk_fma_f32 v[162:163], v[144:145], v[136:137], v[130:131] op_sel_hi:[1,0,1]
	s_waitcnt lgkmcnt(6)
	v_pk_mul_f32 v[0:1], v[0:1], v[28:29]
	v_fmac_f32_e32 v132, v141, v136
	v_pk_mul_f32 v[2:3], v[2:3], v[162:163]
	s_waitcnt lgkmcnt(1)
	v_pk_fma_f32 v[0:1], v[154:155], v[134:135], v[0:1] op_sel_hi:[1,0,1]
	ds_write_b32 v109, v132 offset:50368
	v_pk_mul_f32 v[122:123], v[122:123], v[28:29]
	v_pk_fma_f32 v[2:3], v[156:157], v[134:135], v[2:3] op_sel_hi:[1,0,1]
	v_pk_mul_f32 v[28:29], v[158:159], v[0:1]
	ds_read_b128 v[130:133], v26 offset:20176
	ds_read_b128 v[136:139], v26 offset:20432
	ds_read_b128 v[142:145], v26 offset:20688
	ds_read_b128 v[146:149], v26 offset:20944
	ds_read_b128 v[150:153], v26 offset:21200
	ds_read_b32 v166, v27 offset:21456
	ds_read_b32 v141, v6 offset:21712
	v_pk_fma_f32 v[122:123], v[124:125], v[162:163], v[122:123]
	v_pk_fma_f32 v[28:29], v[160:161], v[2:3], v[28:29]
	v_add_f32_e32 v122, v122, v123
	v_add_f32_e32 v28, v28, v29
	s_nop 0
	v_add_f32_dpp v122, v122, v122 row_ror:8 row_mask:0xf bank_mask:0xf
	v_add_f32_dpp v28, v28, v28 row_ror:8 row_mask:0xf bank_mask:0xf
	s_nop 0
	v_add_f32_dpp v122, v122, v122 row_ror:4 row_mask:0xf bank_mask:0xf
	v_add_f32_dpp v28, v28, v28 row_ror:4 row_mask:0xf bank_mask:0xf
	s_nop 0
	v_add_f32_dpp v122, v122, v122 row_ror:2 row_mask:0xf bank_mask:0xf
	v_add_f32_dpp v28, v28, v28 row_ror:2 row_mask:0xf bank_mask:0xf
	s_nop 0
	v_add_f32_dpp v122, v122, v122 row_ror:1 row_mask:0xf bank_mask:0xf
	v_add_f32_dpp v28, v28, v28 row_ror:1 row_mask:0xf bank_mask:0xf
	s_waitcnt vmcnt(4)
	v_mov_b32_e32 v253, v112
	v_lshlrev_b32_e32 v112, 16, v112
	v_pk_fma_f32 v[0:1], v[126:127], v[122:123], v[0:1] op_sel_hi:[1,0,1]
	v_pk_fma_f32 v[2:3], v[128:129], v[122:123], v[2:3] op_sel_hi:[1,0,1]
	s_waitcnt lgkmcnt(5)
	v_pk_mul_f32 v[136:137], v[136:137], v[0:1]
	v_pk_mul_f32 v[0:1], v[130:131], v[0:1]
	v_pk_fma_f32 v[136:137], v[138:139], v[2:3], v[136:137]
	v_pk_mul_f32 v[2:3], v[132:133], v[2:3]
	s_waitcnt lgkmcnt(1)
	v_pk_fma_f32 v[0:1], v[146:147], v[166:167], v[0:1] op_sel_hi:[1,0,1]
	v_pk_fma_f32 v[2:3], v[148:149], v[166:167], v[2:3] op_sel_hi:[1,0,1]
	v_pk_mul_f32 v[130:131], v[150:151], v[0:1]
	v_fmac_f32_e32 v28, v121, v122
	v_pk_fma_f32 v[130:131], v[152:153], v[2:3], v[130:131]
	ds_write_b32 v109, v28 offset:50432
	v_add_f32_e32 v134, v136, v137
	v_add_f32_e32 v29, v130, v131
	ds_read_b128 v[122:125], v26 offset:21728
	ds_read_b128 v[126:129], v26 offset:21984
	ds_read_b128 v[154:157], v26 offset:22240
	ds_read_b128 v[158:161], v26 offset:22496
	ds_read_b128 v[162:165], v26 offset:22752
	ds_read_b32 v28, v27 offset:23008
	ds_read_b32 v121, v6 offset:23264
	s_nop 0
	v_add_f32_dpp v134, v134, v134 row_ror:8 row_mask:0xf bank_mask:0xf
	v_add_f32_dpp v29, v29, v29 row_ror:8 row_mask:0xf bank_mask:0xf
	s_nop 0
	v_add_f32_dpp v134, v134, v134 row_ror:4 row_mask:0xf bank_mask:0xf
	v_add_f32_dpp v29, v29, v29 row_ror:4 row_mask:0xf bank_mask:0xf
	s_nop 0
	v_add_f32_dpp v134, v134, v134 row_ror:2 row_mask:0xf bank_mask:0xf
	v_add_f32_dpp v29, v29, v29 row_ror:2 row_mask:0xf bank_mask:0xf
	s_nop 0
	v_add_f32_dpp v134, v134, v134 row_ror:1 row_mask:0xf bank_mask:0xf
	v_add_f32_dpp v29, v29, v29 row_ror:1 row_mask:0xf bank_mask:0xf
	s_waitcnt vmcnt(0)
	v_lshlrev_b32_e32 v110, 16, v110
	s_waitcnt lgkmcnt(8)
	v_fmac_f32_e32 v29, v141, v134
	v_pk_fma_f32 v[150:151], v[142:143], v[134:135], v[0:1] op_sel_hi:[1,0,1]
	ds_write_b32 v109, v29 offset:50496
	v_pk_fma_f32 v[152:153], v[144:145], v[134:135], v[2:3] op_sel_hi:[1,0,1]
	ds_read_b128 v[130:133], v26 offset:23280
	ds_read_b128 v[136:139], v26 offset:23536
	ds_read_b128 v[0:3], v26 offset:23792
	ds_read_b128 v[142:145], v26 offset:24048
	ds_read_b128 v[146:149], v26 offset:24304
	ds_read_b32 v134, v27 offset:24560
	ds_read_b32 v141, v6 offset:24816
	s_waitcnt lgkmcnt(13)
	v_pk_mul_f32 v[26:27], v[126:127], v[150:151]
	v_lshlrev_b32_e32 v111, 16, v111
	v_pk_fma_f32 v[26:27], v[128:129], v[152:153], v[26:27]
	v_mul_f32_e32 v110, 0x3fb8aa3b, v110
	v_add_f32_e32 v6, v26, v27
	v_pk_mul_f32 v[26:27], v[122:123], v[150:151]
	v_pk_mul_f32 v[122:123], v[124:125], v[152:153]
	s_waitcnt lgkmcnt(9)
	v_pk_fma_f32 v[26:27], v[158:159], v[28:29], v[26:27] op_sel_hi:[1,0,1]
	v_pk_fma_f32 v[28:29], v[160:161], v[28:29], v[122:123] op_sel_hi:[1,0,1]
	v_pk_mul_f32 v[122:123], v[162:163], v[26:27]
	v_exp_f32_e32 v110, v110
	v_pk_fma_f32 v[122:123], v[164:165], v[28:29], v[122:123]
	s_nop 0
	v_add_f32_e32 v122, v122, v123
	s_nop 0
	v_add_f32_dpp v6, v6, v6 row_ror:8 row_mask:0xf bank_mask:0xf
	v_add_f32_dpp v122, v122, v122 row_ror:8 row_mask:0xf bank_mask:0xf
	s_nop 0
	v_add_f32_dpp v6, v6, v6 row_ror:4 row_mask:0xf bank_mask:0xf
	v_add_f32_dpp v122, v122, v122 row_ror:4 row_mask:0xf bank_mask:0xf
	s_nop 0
	v_add_f32_dpp v6, v6, v6 row_ror:2 row_mask:0xf bank_mask:0xf
	v_add_f32_dpp v122, v122, v122 row_ror:2 row_mask:0xf bank_mask:0xf
	s_nop 0
	v_add_f32_dpp v6, v6, v6 row_ror:1 row_mask:0xf bank_mask:0xf
	v_add_f32_dpp v122, v122, v122 row_ror:1 row_mask:0xf bank_mask:0xf
	v_pk_fma_f32 v[26:27], v[154:155], v[6:7], v[26:27] op_sel_hi:[1,0,1]
	s_waitcnt lgkmcnt(8)
	v_fmac_f32_e32 v122, v121, v6
	v_pk_fma_f32 v[28:29], v[156:157], v[6:7], v[28:29] op_sel_hi:[1,0,1]
	ds_write_b32 v109, v122 offset:50560
	s_waitcnt lgkmcnt(6)
	v_pk_mul_f32 v[122:123], v[136:137], v[26:27]
	v_pk_mul_f32 v[26:27], v[130:131], v[26:27]
	v_pk_fma_f32 v[122:123], v[138:139], v[28:29], v[122:123]
	v_pk_mul_f32 v[28:29], v[132:133], v[28:29]
	s_waitcnt lgkmcnt(2)
	v_pk_fma_f32 v[26:27], v[142:143], v[134:135], v[26:27] op_sel_hi:[1,0,1]
	v_add_f32_e32 v6, v122, v123
	v_pk_fma_f32 v[28:29], v[144:145], v[134:135], v[28:29] op_sel_hi:[1,0,1]
	v_pk_mul_f32 v[122:123], v[146:147], v[26:27]
	s_nop 0
	v_pk_fma_f32 v[122:123], v[148:149], v[28:29], v[122:123]
	s_nop 0
	v_add_f32_e32 v121, v122, v123
	s_nop 0
	v_add_f32_dpp v6, v6, v6 row_ror:8 row_mask:0xf bank_mask:0xf
	v_add_f32_dpp v121, v121, v121 row_ror:8 row_mask:0xf bank_mask:0xf
	s_nop 0
	v_add_f32_dpp v6, v6, v6 row_ror:4 row_mask:0xf bank_mask:0xf
	v_add_f32_dpp v121, v121, v121 row_ror:4 row_mask:0xf bank_mask:0xf
	s_nop 0
	v_add_f32_dpp v6, v6, v6 row_ror:2 row_mask:0xf bank_mask:0xf
	v_add_f32_dpp v121, v121, v121 row_ror:2 row_mask:0xf bank_mask:0xf
	s_nop 0
	v_add_f32_dpp v6, v6, v6 row_ror:1 row_mask:0xf bank_mask:0xf
	v_add_f32_dpp v121, v121, v121 row_ror:1 row_mask:0xf bank_mask:0xf
	s_waitcnt lgkmcnt(1)
	v_fmac_f32_e32 v121, v141, v6
	ds_write_b32 v109, v121 offset:50624
	v_lshlrev_b32_e32 v109, 16, v120
	v_sub_f32_e32 v109, v109, v119
	v_fmac_f32_e32 v119, v32, v109
	v_lshlrev_b32_e32 v109, 16, v117
	v_sub_f32_e32 v109, v109, v116
	v_fmac_f32_e32 v116, v34, v109
	v_lshlrev_b32_e32 v109, 16, v113
	v_lshlrev_b32_e32 v113, 16, v114
	v_sub_f32_e32 v109, v109, v112
	v_sub_f32_e32 v113, v113, v112
	v_fmac_f32_e32 v112, v11, v109
	v_add_f32_e32 v109, -1.0, v111
	v_fmac_f32_e32 v116, v35, v115
	v_fma_f32 v109, v76, v109, 1.0
	v_fmac_f32_e32 v112, v30, v113
	v_mul_f32_e32 v113, v116, v109
	v_add_u32_e32 v109, s23, v43
	v_mul_f32_e64 v115, v75, -v116
	v_lshl_add_u32 v114, v182, 2, v109
	v_mul_f32_e32 v22, v22, v115
	ds_write2st64_b32 v114, v110, v22 offset1:1
	v_mul_f32_e64 v22, -v22, v111
	v_fmac_f32_e32 v119, v33, v118
	ds_write2st64_b32 v114, v22, v113 offset0:2 offset1:3
	ds_write2st64_b32 v114, v119, v112 offset0:4 offset1:5
	s_and_saveexec_b64 s[18:19], s[6:7]
	ds_write_b32 v109, v23 offset:1536
	s_or_b64 exec, exec, s[18:19]
	v_cndmask_b32_e32 v105, v102, v251, vcc
	v_cndmask_b32_e32 v106, v251, v102, vcc
	v_cndmask_b32_e32 v99, v103, v252, vcc
	v_cndmask_b32_e32 v96, v252, v103, vcc
	v_cndmask_b32_e32 v87, v93, v253, vcc
	v_cndmask_b32_e32 v83, v253, v93, vcc
	v_cndmask_b32_e32 v107, v82, v101, vcc
	v_cndmask_b32_e32 v108, v101, v82, vcc
	v_cndmask_b32_e32 v104, v89, v98, vcc
	v_cndmask_b32_e32 v100, v98, v89, vcc
	v_cndmask_b32_e32 v94, v78, v86, vcc
	v_cndmask_b32_e32 v91, v86, v78, vcc
	v_lshlrev_b32_e32 v22, 16, v105
	v_lshlrev_b32_e32 v23, 16, v101
	v_lshlrev_b32_e32 v101, 16, v106
	v_sub_f32_e32 v22, v22, v23
	v_sub_f32_e32 v101, v101, v23
	v_fmac_f32_e32 v23, v32, v22
	v_lshlrev_b32_e32 v22, 16, v99
	v_lshlrev_b32_e32 v98, 16, v98
	v_lshlrev_b32_e32 v96, 16, v96
	v_sub_f32_e32 v22, v22, v98
	v_sub_f32_e32 v96, v96, v98
	v_fmac_f32_e32 v98, v34, v22
	v_lshlrev_b32_e32 v22, 16, v87
	v_lshlrev_b32_e32 v86, 16, v86
	v_lshlrev_b32_e32 v83, 16, v83
	v_sub_f32_e32 v22, v22, v86
	v_sub_f32_e32 v83, v83, v86
	v_fmac_f32_e32 v86, v11, v22
	v_lshlrev_b32_e32 v85, 16, v85
	v_fmac_f32_e32 v86, v30, v83
	v_lshlrev_b32_e32 v83, 16, v97
	v_mul_f32_e32 v85, 0x3fb8aa3b, v85
	v_add_f32_e32 v22, -1.0, v83
	v_exp_f32_e32 v85, v85
	v_fmac_f32_e32 v98, v35, v96
	v_fma_f32 v22, v76, v22, 1.0
	v_mul_f32_e32 v87, v98, v22
	v_add_u32_e32 v22, s23, v45
	v_mul_f32_e64 v97, v75, -v98
	v_lshl_add_u32 v96, v182, 2, v22
	v_mul_f32_e32 v24, v24, v97
	ds_write2st64_b32 v96, v85, v24 offset1:1
	v_mul_f32_e64 v24, -v24, v83
	v_fmac_f32_e32 v23, v33, v101
	ds_write2st64_b32 v96, v24, v87 offset0:2 offset1:3
	ds_write2st64_b32 v96, v23, v86 offset0:4 offset1:5
	s_and_saveexec_b64 s[10:11], s[6:7]
	ds_write_b32 v22, v25 offset:1536
	s_or_b64 exec, exec, s[10:11]
	v_lshlrev_b32_e32 v22, 16, v107
	v_lshlrev_b32_e32 v23, 16, v102
	v_lshlrev_b32_e32 v24, 16, v108
	v_sub_f32_e32 v22, v22, v23
	v_sub_f32_e32 v24, v24, v23
	v_fmac_f32_e32 v23, v32, v22
	v_lshlrev_b32_e32 v22, 16, v104
	v_fmac_f32_e32 v23, v33, v24
	v_lshlrev_b32_e32 v24, 16, v103
	v_lshlrev_b32_e32 v25, 16, v100
	v_sub_f32_e32 v22, v22, v24
	v_sub_f32_e32 v25, v25, v24
	v_fmac_f32_e32 v24, v34, v22
	v_lshlrev_b32_e32 v22, 16, v94
	v_fmac_f32_e32 v24, v35, v25
	v_lshlrev_b32_e32 v25, 16, v93
	v_lshlrev_b32_e32 v83, 16, v91
	v_sub_f32_e32 v22, v22, v25
	v_sub_f32_e32 v83, v83, v25
	v_fmac_f32_e32 v25, v11, v22
	v_lshlrev_b32_e32 v81, 16, v81
	v_fmac_f32_e32 v25, v30, v83
	v_lshlrev_b32_e32 v83, 16, v95
	v_mul_f32_e32 v81, 0x3fb8aa3b, v81
	v_add_f32_e32 v22, -1.0, v83
	v_exp_f32_e32 v81, v81
	v_fma_f32 v22, v76, v22, 1.0
	v_mul_f32_e32 v85, v24, v22
	v_add_u32_e32 v22, s23, v47
	v_mul_f32_e64 v24, v75, -v24
	v_lshl_add_u32 v86, v182, 2, v22
	v_mul_f32_e32 v20, v20, v24
	ds_write2st64_b32 v86, v81, v20 offset1:1
	v_mul_f32_e64 v20, -v20, v83
	ds_write2st64_b32 v86, v20, v85 offset0:2 offset1:3
	ds_write2st64_b32 v86, v23, v25 offset0:4 offset1:5
	s_and_saveexec_b64 s[10:11], s[6:7]
	ds_write_b32 v22, v21 offset:1536
	s_or_b64 exec, exec, s[10:11]
	v_add_u32_e32 v20, s29, v64
	v_add_u32_e32 v21, s28, v68
	v_cndmask_b32_e32 v20, v21, v20, vcc
	v_lshlrev_b32_e32 v22, 16, v92
	v_cmp_lt_i32_e64 s[10:11], 0, v20
	v_lshlrev_b32_e32 v21, 16, v82
	v_lshlrev_b32_e32 v23, 16, v88
	v_cndmask_b32_e64 v22, 0, v22, s[10:11]
	v_cmp_gt_i32_e64 s[12:13], s94, v20
	v_sub_f32_e32 v22, v22, v21
	v_lshlrev_b32_e32 v24, 16, v77
	v_cndmask_b32_e64 v20, 0, v23, s[12:13]
	v_sub_f32_e32 v20, v20, v21
	v_fmac_f32_e32 v21, v32, v22
	v_fmac_f32_e32 v21, v33, v20
	v_lshlrev_b32_e32 v20, 16, v90
	v_lshlrev_b32_e32 v22, 16, v89
	v_cndmask_b32_e64 v20, 0, v20, s[10:11]
	v_lshlrev_b32_e32 v23, 16, v84
	v_sub_f32_e32 v20, v20, v22
	v_cndmask_b32_e64 v23, 0, v23, s[12:13]
	v_sub_f32_e32 v23, v23, v22
	v_fmac_f32_e32 v22, v34, v20
	v_lshlrev_b32_e32 v20, 16, v79
	v_fmac_f32_e32 v22, v35, v23
	v_lshlrev_b32_e32 v23, 16, v78
	v_cndmask_b32_e64 v20, 0, v20, s[10:11]
	v_sub_f32_e32 v20, v20, v23
	v_cndmask_b32_e64 v24, 0, v24, s[12:13]
	v_sub_f32_e32 v24, v24, v23
	v_fmac_f32_e32 v23, v11, v20
	v_lshlrev_b32_e32 v9, 16, v9
	v_fmac_f32_e32 v23, v30, v24
	v_lshlrev_b32_e32 v24, 16, v80
	v_mul_f32_e32 v9, 0x3fb8aa3b, v9
	v_add_f32_e32 v20, -1.0, v24
	v_exp_f32_e32 v9, v9
	v_fma_f32 v20, v76, v20, 1.0
	v_mul_f32_e32 v25, v22, v20
	v_add_u32_e32 v20, s23, v49
	v_mul_f32_e64 v22, v75, -v22
	v_lshl_add_u32 v77, v182, 2, v20
	v_mul_f32_e32 v18, v18, v22
	ds_write2st64_b32 v77, v9, v18 offset1:1
	v_mul_f32_e64 v9, -v18, v24
	ds_write2st64_b32 v77, v9, v25 offset0:2 offset1:3
	ds_write2st64_b32 v77, v21, v23 offset0:4 offset1:5
	s_and_saveexec_b64 s[10:11], s[6:7]
	s_cbranch_execz .LBB0_1982
	ds_write_b32 v20, v19 offset:1536
	s_branch .LBB0_1982
